# GEMM k-loops: stage flip, M0 and first piece address computed before the barrier so the first LDS-DMA piece issues immediately after it
# baseline (speedup 1.0000x reference)
.Lg0_top:
	s_xor_b32 s87, s87, 0x10000
	s_mov_b32 m0, s87
	s_add_u32 s88, s60, s16
	s_addc_u32 s89, s61, s17
	s_waitcnt lgkmcnt(0)
	s_waitcnt vmcnt(0)
	s_barrier
	global_load_lds_dwordx4 v144, s[88:89]
	ds_read_b128 v[156:159], v143
	ds_read_b128 v[160:163], v143 offset:2048
	ds_read_b128 v[164:167], v143 offset:4096
	ds_read_b128 v[168:171], v143 offset:6144
	ds_read_b128 v[190:193], v180 offset:32768
	ds_read_b128 v[194:197], v180 offset:34816
	ds_read_b128 v[198:201], v180 offset:36864
	ds_read_b128 v[202:205], v180 offset:38912
	v_mfma_f32_16x16x32_bf16 v[60:63], v[172:175], v[206:209], v[60:63]
	v_mfma_f32_16x16x32_bf16 v[52:55], v[172:175], v[210:213], v[52:55]
	s_add_u32 m0, s87, 0x2000
	s_add_u32 s88, s60, s18
	s_addc_u32 s89, s61, s19
	global_load_lds_dwordx4 v144, s[88:89]
	v_mfma_f32_16x16x32_bf16 v[56:59], v[172:175], v[214:217], v[56:59]
	v_mfma_f32_16x16x32_bf16 v[48:51], v[172:175], v[218:221], v[48:51]
	s_add_u32 m0, s87, 0x4000
	s_add_u32 s88, s60, s22
	s_addc_u32 s89, s61, s23
	global_load_lds_dwordx4 v144, s[88:89]
	v_mfma_f32_16x16x32_bf16 v[44:47], v[176:179], v[206:209], v[44:47]
	v_mfma_f32_16x16x32_bf16 v[36:39], v[176:179], v[210:213], v[36:39]
	s_add_u32 m0, s87, 0x6000
	s_add_u32 s88, s60, s40
	s_addc_u32 s89, s61, s41
	global_load_lds_dwordx4 v144, s[88:89]
	v_mfma_f32_16x16x32_bf16 v[40:43], v[176:179], v[214:217], v[40:43]
	v_mfma_f32_16x16x32_bf16 v[32:35], v[176:179], v[218:221], v[32:35]
	s_add_u32 m0, s87, 0x8000
	s_add_u32 s88, s60, s42
	s_addc_u32 s89, s61, s43
	global_load_lds_dwordx4 v145, s[88:89]
	v_mfma_f32_16x16x32_bf16 v[28:31], v[182:185], v[206:209], v[28:31]
	v_mfma_f32_16x16x32_bf16 v[16:19], v[182:185], v[210:213], v[16:19]
	s_add_u32 m0, s87, 0xa000
	s_add_u32 s88, s60, s52
	s_addc_u32 s89, s61, s53
	global_load_lds_dwordx4 v145, s[88:89]
	v_mfma_f32_16x16x32_bf16 v[24:27], v[182:185], v[214:217], v[24:27]
	v_mfma_f32_16x16x32_bf16 v[12:15], v[182:185], v[218:221], v[12:15]
	s_add_u32 m0, s87, 0xc000
	s_add_u32 s88, s60, s54
	s_addc_u32 s89, s61, s55
	global_load_lds_dwordx4 v145, s[88:89]
	v_mfma_f32_16x16x32_bf16 v[4:7], v[186:189], v[206:209], v[4:7]
	v_mfma_f32_16x16x32_bf16 v[0:3], v[186:189], v[210:213], v[0:3]
	s_add_u32 m0, s87, 0xe000
	s_add_u32 s88, s60, s56
	s_addc_u32 s89, s61, s57
	global_load_lds_dwordx4 v145, s[88:89]
	v_mfma_f32_16x16x32_bf16 v[20:23], v[186:189], v[214:217], v[20:23]
	v_mfma_f32_16x16x32_bf16 v[8:11], v[186:189], v[218:221], v[8:11]
.Lg0_entry:
	ds_read_b128 v[172:175], v143 offset:8192
	ds_read_b128 v[176:179], v143 offset:10240
	ds_read_b128 v[182:185], v143 offset:12288
	ds_read_b128 v[186:189], v143 offset:14336
	s_waitcnt lgkmcnt(4)
	v_mfma_f32_16x16x32_bf16 v[124:127], v[156:159], v[190:193], v[124:127]
	v_mfma_f32_16x16x32_bf16 v[116:119], v[156:159], v[194:197], v[116:119]
	v_mfma_f32_16x16x32_bf16 v[120:123], v[156:159], v[198:201], v[120:123]
	v_mfma_f32_16x16x32_bf16 v[112:115], v[156:159], v[202:205], v[112:115]
	v_mfma_f32_16x16x32_bf16 v[108:111], v[160:163], v[190:193], v[108:111]
	v_mfma_f32_16x16x32_bf16 v[100:103], v[160:163], v[194:197], v[100:103]
	v_mfma_f32_16x16x32_bf16 v[104:107], v[160:163], v[198:201], v[104:107]
	v_mfma_f32_16x16x32_bf16 v[96:99], v[160:163], v[202:205], v[96:99]
	v_mfma_f32_16x16x32_bf16 v[92:95], v[164:167], v[190:193], v[92:95]
	v_mfma_f32_16x16x32_bf16 v[84:87], v[164:167], v[194:197], v[84:87]
	v_mfma_f32_16x16x32_bf16 v[88:91], v[164:167], v[198:201], v[88:91]
	v_mfma_f32_16x16x32_bf16 v[80:83], v[164:167], v[202:205], v[80:83]
	v_mfma_f32_16x16x32_bf16 v[76:79], v[168:171], v[190:193], v[76:79]
	v_mfma_f32_16x16x32_bf16 v[68:71], v[168:171], v[194:197], v[68:71]
	v_mfma_f32_16x16x32_bf16 v[72:75], v[168:171], v[198:201], v[72:75]
	v_mfma_f32_16x16x32_bf16 v[64:67], v[168:171], v[202:205], v[64:67]
	ds_read_b128 v[156:159], v155
	ds_read_b128 v[160:163], v155 offset:2048
	ds_read_b128 v[164:167], v155 offset:4096
	ds_read_b128 v[168:171], v155 offset:6144
	ds_read_b128 v[206:209], v222 offset:32768
	ds_read_b128 v[210:213], v222 offset:34816
	ds_read_b128 v[214:217], v222 offset:36864
	ds_read_b128 v[218:221], v222 offset:38912
	s_waitcnt lgkmcnt(8)
	v_mfma_f32_16x16x32_bf16 v[60:63], v[172:175], v[190:193], v[60:63]
	v_mfma_f32_16x16x32_bf16 v[52:55], v[172:175], v[194:197], v[52:55]
	v_mfma_f32_16x16x32_bf16 v[56:59], v[172:175], v[198:201], v[56:59]
	v_mfma_f32_16x16x32_bf16 v[48:51], v[172:175], v[202:205], v[48:51]
	v_mfma_f32_16x16x32_bf16 v[44:47], v[176:179], v[190:193], v[44:47]
	v_mfma_f32_16x16x32_bf16 v[36:39], v[176:179], v[194:197], v[36:39]
	v_mfma_f32_16x16x32_bf16 v[40:43], v[176:179], v[198:201], v[40:43]
	v_mfma_f32_16x16x32_bf16 v[32:35], v[176:179], v[202:205], v[32:35]
	v_mfma_f32_16x16x32_bf16 v[28:31], v[182:185], v[190:193], v[28:31]
	v_mfma_f32_16x16x32_bf16 v[16:19], v[182:185], v[194:197], v[16:19]
	v_mfma_f32_16x16x32_bf16 v[24:27], v[182:185], v[198:201], v[24:27]
	v_mfma_f32_16x16x32_bf16 v[12:15], v[182:185], v[202:205], v[12:15]
	v_mfma_f32_16x16x32_bf16 v[4:7], v[186:189], v[190:193], v[4:7]
	v_mfma_f32_16x16x32_bf16 v[0:3], v[186:189], v[194:197], v[0:3]
	v_mfma_f32_16x16x32_bf16 v[20:23], v[186:189], v[198:201], v[20:23]
	v_mfma_f32_16x16x32_bf16 v[8:11], v[186:189], v[202:205], v[8:11]
	ds_read_b128 v[172:175], v155 offset:8192
	ds_read_b128 v[176:179], v155 offset:10240
	ds_read_b128 v[182:185], v155 offset:12288
	ds_read_b128 v[186:189], v155 offset:14336
	s_waitcnt lgkmcnt(4)
	v_mfma_f32_16x16x32_bf16 v[124:127], v[156:159], v[206:209], v[124:127]
	v_mfma_f32_16x16x32_bf16 v[116:119], v[156:159], v[210:213], v[116:119]
	v_mfma_f32_16x16x32_bf16 v[120:123], v[156:159], v[214:217], v[120:123]
	v_mfma_f32_16x16x32_bf16 v[112:115], v[156:159], v[218:221], v[112:115]
	v_mfma_f32_16x16x32_bf16 v[108:111], v[160:163], v[206:209], v[108:111]
	v_mfma_f32_16x16x32_bf16 v[100:103], v[160:163], v[210:213], v[100:103]
	v_mfma_f32_16x16x32_bf16 v[104:107], v[160:163], v[214:217], v[104:107]
	v_mfma_f32_16x16x32_bf16 v[96:99], v[160:163], v[218:221], v[96:99]
	v_mfma_f32_16x16x32_bf16 v[92:95], v[164:167], v[206:209], v[92:95]
	v_mfma_f32_16x16x32_bf16 v[84:87], v[164:167], v[210:213], v[84:87]
	v_mfma_f32_16x16x32_bf16 v[88:91], v[164:167], v[214:217], v[88:91]
	v_mfma_f32_16x16x32_bf16 v[80:83], v[164:167], v[218:221], v[80:83]
	v_mfma_f32_16x16x32_bf16 v[76:79], v[168:171], v[206:209], v[76:79]
	v_mfma_f32_16x16x32_bf16 v[68:71], v[168:171], v[210:213], v[68:71]
	v_mfma_f32_16x16x32_bf16 v[72:75], v[168:171], v[214:217], v[72:75]
	v_mfma_f32_16x16x32_bf16 v[64:67], v[168:171], v[218:221], v[64:67]
	s_add_u32 s60, s60, 0x80
	s_addc_u32 s61, s61, 0
	s_add_i32 s59, s59, 1
	s_cmp_lt_u32 s59, 15
	s_cbranch_scc0 .Lg0_last
	s_xor_b32 s87, s87, 0x10000
	s_mov_b32 m0, s87
	s_add_u32 s88, s60, s16
	s_addc_u32 s89, s61, s17
	s_waitcnt lgkmcnt(0)
	s_waitcnt vmcnt(0)
	s_barrier
	global_load_lds_dwordx4 v144, s[88:89]
	ds_read_b128 v[156:159], v223
	ds_read_b128 v[160:163], v223 offset:2048
	ds_read_b128 v[164:167], v223 offset:4096
	ds_read_b128 v[168:171], v223 offset:6144
	ds_read_b128 v[190:193], v225 offset:32768
	ds_read_b128 v[194:197], v225 offset:34816
	ds_read_b128 v[198:201], v225 offset:36864
	ds_read_b128 v[202:205], v225 offset:38912
	v_mfma_f32_16x16x32_bf16 v[60:63], v[172:175], v[206:209], v[60:63]
	v_mfma_f32_16x16x32_bf16 v[52:55], v[172:175], v[210:213], v[52:55]
	s_add_u32 m0, s87, 0x2000
	s_add_u32 s88, s60, s18
	s_addc_u32 s89, s61, s19
	global_load_lds_dwordx4 v144, s[88:89]
	v_mfma_f32_16x16x32_bf16 v[56:59], v[172:175], v[214:217], v[56:59]
	v_mfma_f32_16x16x32_bf16 v[48:51], v[172:175], v[218:221], v[48:51]
	s_add_u32 m0, s87, 0x4000
	s_add_u32 s88, s60, s22
	s_addc_u32 s89, s61, s23
	global_load_lds_dwordx4 v144, s[88:89]
	v_mfma_f32_16x16x32_bf16 v[44:47], v[176:179], v[206:209], v[44:47]
	v_mfma_f32_16x16x32_bf16 v[36:39], v[176:179], v[210:213], v[36:39]
	s_add_u32 m0, s87, 0x6000
	s_add_u32 s88, s60, s40
	s_addc_u32 s89, s61, s41
	global_load_lds_dwordx4 v144, s[88:89]
	v_mfma_f32_16x16x32_bf16 v[40:43], v[176:179], v[214:217], v[40:43]
	v_mfma_f32_16x16x32_bf16 v[32:35], v[176:179], v[218:221], v[32:35]
	s_add_u32 m0, s87, 0x8000
	s_add_u32 s88, s60, s42
	s_addc_u32 s89, s61, s43
	global_load_lds_dwordx4 v145, s[88:89]
	v_mfma_f32_16x16x32_bf16 v[28:31], v[182:185], v[206:209], v[28:31]
	v_mfma_f32_16x16x32_bf16 v[16:19], v[182:185], v[210:213], v[16:19]
	s_add_u32 m0, s87, 0xa000
	s_add_u32 s88, s60, s52
	s_addc_u32 s89, s61, s53
	global_load_lds_dwordx4 v145, s[88:89]
	v_mfma_f32_16x16x32_bf16 v[24:27], v[182:185], v[214:217], v[24:27]
	v_mfma_f32_16x16x32_bf16 v[12:15], v[182:185], v[218:221], v[12:15]
	s_add_u32 m0, s87, 0xc000
	s_add_u32 s88, s60, s54
	s_addc_u32 s89, s61, s55
	global_load_lds_dwordx4 v145, s[88:89]
	v_mfma_f32_16x16x32_bf16 v[4:7], v[186:189], v[206:209], v[4:7]
	v_mfma_f32_16x16x32_bf16 v[0:3], v[186:189], v[210:213], v[0:3]
	s_add_u32 m0, s87, 0xe000
	s_add_u32 s88, s60, s56
	s_addc_u32 s89, s61, s57
	global_load_lds_dwordx4 v145, s[88:89]
	v_mfma_f32_16x16x32_bf16 v[20:23], v[186:189], v[214:217], v[20:23]
	v_mfma_f32_16x16x32_bf16 v[8:11], v[186:189], v[218:221], v[8:11]
	ds_read_b128 v[172:175], v223 offset:8192
	ds_read_b128 v[176:179], v223 offset:10240
	ds_read_b128 v[182:185], v223 offset:12288
	ds_read_b128 v[186:189], v223 offset:14336
	s_waitcnt lgkmcnt(4)
	v_mfma_f32_16x16x32_bf16 v[124:127], v[156:159], v[190:193], v[124:127]
	v_mfma_f32_16x16x32_bf16 v[116:119], v[156:159], v[194:197], v[116:119]
	v_mfma_f32_16x16x32_bf16 v[120:123], v[156:159], v[198:201], v[120:123]
	v_mfma_f32_16x16x32_bf16 v[112:115], v[156:159], v[202:205], v[112:115]
	v_mfma_f32_16x16x32_bf16 v[108:111], v[160:163], v[190:193], v[108:111]
	v_mfma_f32_16x16x32_bf16 v[100:103], v[160:163], v[194:197], v[100:103]
	v_mfma_f32_16x16x32_bf16 v[104:107], v[160:163], v[198:201], v[104:107]
	v_mfma_f32_16x16x32_bf16 v[96:99], v[160:163], v[202:205], v[96:99]
	v_mfma_f32_16x16x32_bf16 v[92:95], v[164:167], v[190:193], v[92:95]
	v_mfma_f32_16x16x32_bf16 v[84:87], v[164:167], v[194:197], v[84:87]
	v_mfma_f32_16x16x32_bf16 v[88:91], v[164:167], v[198:201], v[88:91]
	v_mfma_f32_16x16x32_bf16 v[80:83], v[164:167], v[202:205], v[80:83]
	v_mfma_f32_16x16x32_bf16 v[76:79], v[168:171], v[190:193], v[76:79]
	v_mfma_f32_16x16x32_bf16 v[68:71], v[168:171], v[194:197], v[68:71]
	v_mfma_f32_16x16x32_bf16 v[72:75], v[168:171], v[198:201], v[72:75]
	v_mfma_f32_16x16x32_bf16 v[64:67], v[168:171], v[202:205], v[64:67]
	ds_read_b128 v[156:159], v224
	ds_read_b128 v[160:163], v224 offset:2048
	ds_read_b128 v[164:167], v224 offset:4096
	ds_read_b128 v[168:171], v224 offset:6144
	ds_read_b128 v[206:209], v226 offset:32768
	ds_read_b128 v[210:213], v226 offset:34816
	ds_read_b128 v[214:217], v226 offset:36864
	ds_read_b128 v[218:221], v226 offset:38912
	s_waitcnt lgkmcnt(8)
	v_mfma_f32_16x16x32_bf16 v[60:63], v[172:175], v[190:193], v[60:63]
	v_mfma_f32_16x16x32_bf16 v[52:55], v[172:175], v[194:197], v[52:55]
	v_mfma_f32_16x16x32_bf16 v[56:59], v[172:175], v[198:201], v[56:59]
	v_mfma_f32_16x16x32_bf16 v[48:51], v[172:175], v[202:205], v[48:51]
	v_mfma_f32_16x16x32_bf16 v[44:47], v[176:179], v[190:193], v[44:47]
	v_mfma_f32_16x16x32_bf16 v[36:39], v[176:179], v[194:197], v[36:39]
	v_mfma_f32_16x16x32_bf16 v[40:43], v[176:179], v[198:201], v[40:43]
	v_mfma_f32_16x16x32_bf16 v[32:35], v[176:179], v[202:205], v[32:35]
	v_mfma_f32_16x16x32_bf16 v[28:31], v[182:185], v[190:193], v[28:31]
	v_mfma_f32_16x16x32_bf16 v[16:19], v[182:185], v[194:197], v[16:19]
	v_mfma_f32_16x16x32_bf16 v[24:27], v[182:185], v[198:201], v[24:27]
	v_mfma_f32_16x16x32_bf16 v[12:15], v[182:185], v[202:205], v[12:15]
	v_mfma_f32_16x16x32_bf16 v[4:7], v[186:189], v[190:193], v[4:7]
	v_mfma_f32_16x16x32_bf16 v[0:3], v[186:189], v[194:197], v[0:3]
	v_mfma_f32_16x16x32_bf16 v[20:23], v[186:189], v[198:201], v[20:23]
	v_mfma_f32_16x16x32_bf16 v[8:11], v[186:189], v[202:205], v[8:11]
	ds_read_b128 v[172:175], v224 offset:8192
	ds_read_b128 v[176:179], v224 offset:10240
	ds_read_b128 v[182:185], v224 offset:12288
	ds_read_b128 v[186:189], v224 offset:14336
	s_waitcnt lgkmcnt(4)
	v_mfma_f32_16x16x32_bf16 v[124:127], v[156:159], v[206:209], v[124:127]
	v_mfma_f32_16x16x32_bf16 v[116:119], v[156:159], v[210:213], v[116:119]
	v_mfma_f32_16x16x32_bf16 v[120:123], v[156:159], v[214:217], v[120:123]
	v_mfma_f32_16x16x32_bf16 v[112:115], v[156:159], v[218:221], v[112:115]
	v_mfma_f32_16x16x32_bf16 v[108:111], v[160:163], v[206:209], v[108:111]
	v_mfma_f32_16x16x32_bf16 v[100:103], v[160:163], v[210:213], v[100:103]
	v_mfma_f32_16x16x32_bf16 v[104:107], v[160:163], v[214:217], v[104:107]
	v_mfma_f32_16x16x32_bf16 v[96:99], v[160:163], v[218:221], v[96:99]
	v_mfma_f32_16x16x32_bf16 v[92:95], v[164:167], v[206:209], v[92:95]
	v_mfma_f32_16x16x32_bf16 v[84:87], v[164:167], v[210:213], v[84:87]
	v_mfma_f32_16x16x32_bf16 v[88:91], v[164:167], v[214:217], v[88:91]
	v_mfma_f32_16x16x32_bf16 v[80:83], v[164:167], v[218:221], v[80:83]
	v_mfma_f32_16x16x32_bf16 v[76:79], v[168:171], v[206:209], v[76:79]
	v_mfma_f32_16x16x32_bf16 v[68:71], v[168:171], v[210:213], v[68:71]
	v_mfma_f32_16x16x32_bf16 v[72:75], v[168:171], v[214:217], v[72:75]
	v_mfma_f32_16x16x32_bf16 v[64:67], v[168:171], v[218:221], v[64:67]
	s_add_u32 s60, s60, 0x80
	s_addc_u32 s61, s61, 0
	s_add_i32 s59, s59, 1
	s_branch .Lg0_top

.Lg1_top:
	s_xor_b32 s59, s59, 0x10000
	s_mov_b32 m0, s59
	s_add_u32 s52, s50, s14
	s_addc_u32 s53, s51, s15
	s_waitcnt lgkmcnt(0)
	s_waitcnt vmcnt(0)
	s_barrier
	global_load_lds_dwordx4 v178, s[52:53]
	ds_read_b128 v[142:145], v141
	ds_read_b128 v[146:149], v141 offset:2048
	ds_read_b128 v[150:153], v141 offset:4096
	ds_read_b128 v[154:157], v141 offset:6144
	ds_read_b128 v[174:177], v210 offset:32768
	ds_read_b128 v[182:185], v210 offset:34816
	ds_read_b128 v[186:189], v210 offset:36864
	ds_read_b128 v[190:193], v210 offset:38912
	v_mfma_f32_16x16x32_bf16 v[60:63], v[158:161], v[194:197], v[60:63]
	v_mfma_f32_16x16x32_bf16 v[56:59], v[158:161], v[198:201], v[56:59]
	s_add_u32 m0, s59, 0x2000
	s_add_u32 s52, s50, s16
	s_addc_u32 s53, s51, s17
	global_load_lds_dwordx4 v178, s[52:53]
	v_mfma_f32_16x16x32_bf16 v[52:55], v[158:161], v[202:205], v[52:55]
	v_mfma_f32_16x16x32_bf16 v[48:51], v[158:161], v[206:209], v[48:51]
	s_add_u32 m0, s59, 0x4000
	s_add_u32 s52, s50, s18
	s_addc_u32 s53, s51, s19
	global_load_lds_dwordx4 v178, s[52:53]
	v_mfma_f32_16x16x32_bf16 v[44:47], v[162:165], v[194:197], v[44:47]
	v_mfma_f32_16x16x32_bf16 v[40:43], v[162:165], v[198:201], v[40:43]
	s_add_u32 m0, s59, 0x6000
	s_add_u32 s52, s50, s22
	s_addc_u32 s53, s51, s23
	global_load_lds_dwordx4 v178, s[52:53]
	v_mfma_f32_16x16x32_bf16 v[36:39], v[162:165], v[202:205], v[36:39]
	v_mfma_f32_16x16x32_bf16 v[32:35], v[162:165], v[206:209], v[32:35]
	s_add_u32 m0, s59, 0x8000
	s_add_u32 s52, s50, s40
	s_addc_u32 s53, s51, s41
	global_load_lds_dwordx4 v179, s[52:53]
	v_mfma_f32_16x16x32_bf16 v[28:31], v[166:169], v[194:197], v[28:31]
	v_mfma_f32_16x16x32_bf16 v[20:23], v[166:169], v[198:201], v[20:23]
	s_add_u32 m0, s59, 0xa000
	s_add_u32 s52, s50, s42
	s_addc_u32 s53, s51, s43
	global_load_lds_dwordx4 v179, s[52:53]
	v_mfma_f32_16x16x32_bf16 v[16:19], v[166:169], v[202:205], v[16:19]
	v_mfma_f32_16x16x32_bf16 v[8:11], v[166:169], v[206:209], v[8:11]
	s_add_u32 m0, s59, 0xc000
	s_add_u32 s52, s50, s44
	s_addc_u32 s53, s51, s45
	global_load_lds_dwordx4 v179, s[52:53]
	v_mfma_f32_16x16x32_bf16 v[4:7], v[170:173], v[194:197], v[4:7]
	v_mfma_f32_16x16x32_bf16 v[0:3], v[170:173], v[198:201], v[0:3]
	s_add_u32 m0, s59, 0xe000
	s_add_u32 s52, s50, s46
	s_addc_u32 s53, s51, s47
	global_load_lds_dwordx4 v179, s[52:53]
	v_mfma_f32_16x16x32_bf16 v[24:27], v[170:173], v[202:205], v[24:27]
	v_mfma_f32_16x16x32_bf16 v[12:15], v[170:173], v[206:209], v[12:15]
.Lg1_entry:
	ds_read_b128 v[158:161], v141 offset:8192
	ds_read_b128 v[162:165], v141 offset:10240
	ds_read_b128 v[166:169], v141 offset:12288
	ds_read_b128 v[170:173], v141 offset:14336
	s_waitcnt lgkmcnt(4)
	v_mfma_f32_16x16x32_bf16 v[124:127], v[142:145], v[174:177], v[124:127]
	v_mfma_f32_16x16x32_bf16 v[120:123], v[142:145], v[182:185], v[120:123]
	v_mfma_f32_16x16x32_bf16 v[116:119], v[142:145], v[186:189], v[116:119]
	v_mfma_f32_16x16x32_bf16 v[112:115], v[142:145], v[190:193], v[112:115]
	v_mfma_f32_16x16x32_bf16 v[108:111], v[146:149], v[174:177], v[108:111]
	v_mfma_f32_16x16x32_bf16 v[104:107], v[146:149], v[182:185], v[104:107]
	v_mfma_f32_16x16x32_bf16 v[100:103], v[146:149], v[186:189], v[100:103]
	v_mfma_f32_16x16x32_bf16 v[96:99], v[146:149], v[190:193], v[96:99]
	v_mfma_f32_16x16x32_bf16 v[92:95], v[150:153], v[174:177], v[92:95]
	v_mfma_f32_16x16x32_bf16 v[88:91], v[150:153], v[182:185], v[88:91]
	v_mfma_f32_16x16x32_bf16 v[84:87], v[150:153], v[186:189], v[84:87]
	v_mfma_f32_16x16x32_bf16 v[80:83], v[150:153], v[190:193], v[80:83]
	v_mfma_f32_16x16x32_bf16 v[76:79], v[154:157], v[174:177], v[76:79]
	v_mfma_f32_16x16x32_bf16 v[72:75], v[154:157], v[182:185], v[72:75]
	v_mfma_f32_16x16x32_bf16 v[68:71], v[154:157], v[186:189], v[68:71]
	v_mfma_f32_16x16x32_bf16 v[64:67], v[154:157], v[190:193], v[64:67]
	ds_read_b128 v[142:145], v180
	ds_read_b128 v[146:149], v180 offset:2048
	ds_read_b128 v[150:153], v180 offset:4096
	ds_read_b128 v[154:157], v180 offset:6144
	ds_read_b128 v[194:197], v211 offset:32768
	ds_read_b128 v[198:201], v211 offset:34816
	ds_read_b128 v[202:205], v211 offset:36864
	ds_read_b128 v[206:209], v211 offset:38912
	s_waitcnt lgkmcnt(8)
	v_mfma_f32_16x16x32_bf16 v[60:63], v[158:161], v[174:177], v[60:63]
	v_mfma_f32_16x16x32_bf16 v[56:59], v[158:161], v[182:185], v[56:59]
	v_mfma_f32_16x16x32_bf16 v[52:55], v[158:161], v[186:189], v[52:55]
	v_mfma_f32_16x16x32_bf16 v[48:51], v[158:161], v[190:193], v[48:51]
	v_mfma_f32_16x16x32_bf16 v[44:47], v[162:165], v[174:177], v[44:47]
	v_mfma_f32_16x16x32_bf16 v[40:43], v[162:165], v[182:185], v[40:43]
	v_mfma_f32_16x16x32_bf16 v[36:39], v[162:165], v[186:189], v[36:39]
	v_mfma_f32_16x16x32_bf16 v[32:35], v[162:165], v[190:193], v[32:35]
	v_mfma_f32_16x16x32_bf16 v[28:31], v[166:169], v[174:177], v[28:31]
	v_mfma_f32_16x16x32_bf16 v[20:23], v[166:169], v[182:185], v[20:23]
	v_mfma_f32_16x16x32_bf16 v[16:19], v[166:169], v[186:189], v[16:19]
	v_mfma_f32_16x16x32_bf16 v[8:11], v[166:169], v[190:193], v[8:11]
	v_mfma_f32_16x16x32_bf16 v[4:7], v[170:173], v[174:177], v[4:7]
	v_mfma_f32_16x16x32_bf16 v[0:3], v[170:173], v[182:185], v[0:3]
	v_mfma_f32_16x16x32_bf16 v[24:27], v[170:173], v[186:189], v[24:27]
	v_mfma_f32_16x16x32_bf16 v[12:15], v[170:173], v[190:193], v[12:15]
	ds_read_b128 v[158:161], v180 offset:8192
	ds_read_b128 v[162:165], v180 offset:10240
	ds_read_b128 v[166:169], v180 offset:12288
	ds_read_b128 v[170:173], v180 offset:14336
	s_waitcnt lgkmcnt(4)
	v_mfma_f32_16x16x32_bf16 v[124:127], v[142:145], v[194:197], v[124:127]
	v_mfma_f32_16x16x32_bf16 v[120:123], v[142:145], v[198:201], v[120:123]
	v_mfma_f32_16x16x32_bf16 v[116:119], v[142:145], v[202:205], v[116:119]
	v_mfma_f32_16x16x32_bf16 v[112:115], v[142:145], v[206:209], v[112:115]
	v_mfma_f32_16x16x32_bf16 v[108:111], v[146:149], v[194:197], v[108:111]
	v_mfma_f32_16x16x32_bf16 v[104:107], v[146:149], v[198:201], v[104:107]
	v_mfma_f32_16x16x32_bf16 v[100:103], v[146:149], v[202:205], v[100:103]
	v_mfma_f32_16x16x32_bf16 v[96:99], v[146:149], v[206:209], v[96:99]
	v_mfma_f32_16x16x32_bf16 v[92:95], v[150:153], v[194:197], v[92:95]
	v_mfma_f32_16x16x32_bf16 v[88:91], v[150:153], v[198:201], v[88:91]
	v_mfma_f32_16x16x32_bf16 v[84:87], v[150:153], v[202:205], v[84:87]
	v_mfma_f32_16x16x32_bf16 v[80:83], v[150:153], v[206:209], v[80:83]
	v_mfma_f32_16x16x32_bf16 v[76:79], v[154:157], v[194:197], v[76:79]
	v_mfma_f32_16x16x32_bf16 v[72:75], v[154:157], v[198:201], v[72:75]
	v_mfma_f32_16x16x32_bf16 v[68:71], v[154:157], v[202:205], v[68:71]
	v_mfma_f32_16x16x32_bf16 v[64:67], v[154:157], v[206:209], v[64:67]
	s_add_u32 s50, s50, 0x80
	s_addc_u32 s51, s51, 0
	s_add_i32 s49, s49, 1
	s_cmp_lt_u32 s49, 31
	s_cbranch_scc0 .Lg1_last
	s_xor_b32 s59, s59, 0x10000
	s_mov_b32 m0, s59
	s_add_u32 s52, s50, s14
	s_addc_u32 s53, s51, s15
	s_waitcnt lgkmcnt(0)
	s_waitcnt vmcnt(0)
	s_barrier
	global_load_lds_dwordx4 v178, s[52:53]
	ds_read_b128 v[142:145], v212
	ds_read_b128 v[146:149], v212 offset:2048
	ds_read_b128 v[150:153], v212 offset:4096
	ds_read_b128 v[154:157], v212 offset:6144
	ds_read_b128 v[174:177], v214 offset:32768
	ds_read_b128 v[182:185], v214 offset:34816
	ds_read_b128 v[186:189], v214 offset:36864
	ds_read_b128 v[190:193], v214 offset:38912
	v_mfma_f32_16x16x32_bf16 v[60:63], v[158:161], v[194:197], v[60:63]
	v_mfma_f32_16x16x32_bf16 v[56:59], v[158:161], v[198:201], v[56:59]
	s_add_u32 m0, s59, 0x2000
	s_add_u32 s52, s50, s16
	s_addc_u32 s53, s51, s17
	global_load_lds_dwordx4 v178, s[52:53]
	v_mfma_f32_16x16x32_bf16 v[52:55], v[158:161], v[202:205], v[52:55]
	v_mfma_f32_16x16x32_bf16 v[48:51], v[158:161], v[206:209], v[48:51]
	s_add_u32 m0, s59, 0x4000
	s_add_u32 s52, s50, s18
	s_addc_u32 s53, s51, s19
	global_load_lds_dwordx4 v178, s[52:53]
	v_mfma_f32_16x16x32_bf16 v[44:47], v[162:165], v[194:197], v[44:47]
	v_mfma_f32_16x16x32_bf16 v[40:43], v[162:165], v[198:201], v[40:43]
	s_add_u32 m0, s59, 0x6000
	s_add_u32 s52, s50, s22
	s_addc_u32 s53, s51, s23
	global_load_lds_dwordx4 v178, s[52:53]
	v_mfma_f32_16x16x32_bf16 v[36:39], v[162:165], v[202:205], v[36:39]
	v_mfma_f32_16x16x32_bf16 v[32:35], v[162:165], v[206:209], v[32:35]
	s_add_u32 m0, s59, 0x8000
	s_add_u32 s52, s50, s40
	s_addc_u32 s53, s51, s41
	global_load_lds_dwordx4 v179, s[52:53]
	v_mfma_f32_16x16x32_bf16 v[28:31], v[166:169], v[194:197], v[28:31]
	v_mfma_f32_16x16x32_bf16 v[20:23], v[166:169], v[198:201], v[20:23]
	s_add_u32 m0, s59, 0xa000
	s_add_u32 s52, s50, s42
	s_addc_u32 s53, s51, s43
	global_load_lds_dwordx4 v179, s[52:53]
	v_mfma_f32_16x16x32_bf16 v[16:19], v[166:169], v[202:205], v[16:19]
	v_mfma_f32_16x16x32_bf16 v[8:11], v[166:169], v[206:209], v[8:11]
	s_add_u32 m0, s59, 0xc000
	s_add_u32 s52, s50, s44
	s_addc_u32 s53, s51, s45
	global_load_lds_dwordx4 v179, s[52:53]
	v_mfma_f32_16x16x32_bf16 v[4:7], v[170:173], v[194:197], v[4:7]
	v_mfma_f32_16x16x32_bf16 v[0:3], v[170:173], v[198:201], v[0:3]
	s_add_u32 m0, s59, 0xe000
	s_add_u32 s52, s50, s46
	s_addc_u32 s53, s51, s47
	global_load_lds_dwordx4 v179, s[52:53]
	v_mfma_f32_16x16x32_bf16 v[24:27], v[170:173], v[202:205], v[24:27]
	v_mfma_f32_16x16x32_bf16 v[12:15], v[170:173], v[206:209], v[12:15]
	ds_read_b128 v[158:161], v212 offset:8192
	ds_read_b128 v[162:165], v212 offset:10240
	ds_read_b128 v[166:169], v212 offset:12288
	ds_read_b128 v[170:173], v212 offset:14336
	s_waitcnt lgkmcnt(4)
	v_mfma_f32_16x16x32_bf16 v[124:127], v[142:145], v[174:177], v[124:127]
	v_mfma_f32_16x16x32_bf16 v[120:123], v[142:145], v[182:185], v[120:123]
	v_mfma_f32_16x16x32_bf16 v[116:119], v[142:145], v[186:189], v[116:119]
	v_mfma_f32_16x16x32_bf16 v[112:115], v[142:145], v[190:193], v[112:115]
	v_mfma_f32_16x16x32_bf16 v[108:111], v[146:149], v[174:177], v[108:111]
	v_mfma_f32_16x16x32_bf16 v[104:107], v[146:149], v[182:185], v[104:107]
	v_mfma_f32_16x16x32_bf16 v[100:103], v[146:149], v[186:189], v[100:103]
	v_mfma_f32_16x16x32_bf16 v[96:99], v[146:149], v[190:193], v[96:99]
	v_mfma_f32_16x16x32_bf16 v[92:95], v[150:153], v[174:177], v[92:95]
	v_mfma_f32_16x16x32_bf16 v[88:91], v[150:153], v[182:185], v[88:91]
	v_mfma_f32_16x16x32_bf16 v[84:87], v[150:153], v[186:189], v[84:87]
	v_mfma_f32_16x16x32_bf16 v[80:83], v[150:153], v[190:193], v[80:83]
	v_mfma_f32_16x16x32_bf16 v[76:79], v[154:157], v[174:177], v[76:79]
	v_mfma_f32_16x16x32_bf16 v[72:75], v[154:157], v[182:185], v[72:75]
	v_mfma_f32_16x16x32_bf16 v[68:71], v[154:157], v[186:189], v[68:71]
	v_mfma_f32_16x16x32_bf16 v[64:67], v[154:157], v[190:193], v[64:67]
	ds_read_b128 v[142:145], v213
	ds_read_b128 v[146:149], v213 offset:2048
	ds_read_b128 v[150:153], v213 offset:4096
	ds_read_b128 v[154:157], v213 offset:6144
	ds_read_b128 v[194:197], v215 offset:32768
	ds_read_b128 v[198:201], v215 offset:34816
	ds_read_b128 v[202:205], v215 offset:36864
	ds_read_b128 v[206:209], v215 offset:38912
	s_waitcnt lgkmcnt(8)
	v_mfma_f32_16x16x32_bf16 v[60:63], v[158:161], v[174:177], v[60:63]
	v_mfma_f32_16x16x32_bf16 v[56:59], v[158:161], v[182:185], v[56:59]
	v_mfma_f32_16x16x32_bf16 v[52:55], v[158:161], v[186:189], v[52:55]
	v_mfma_f32_16x16x32_bf16 v[48:51], v[158:161], v[190:193], v[48:51]
	v_mfma_f32_16x16x32_bf16 v[44:47], v[162:165], v[174:177], v[44:47]
	v_mfma_f32_16x16x32_bf16 v[40:43], v[162:165], v[182:185], v[40:43]
	v_mfma_f32_16x16x32_bf16 v[36:39], v[162:165], v[186:189], v[36:39]
	v_mfma_f32_16x16x32_bf16 v[32:35], v[162:165], v[190:193], v[32:35]
	v_mfma_f32_16x16x32_bf16 v[28:31], v[166:169], v[174:177], v[28:31]
	v_mfma_f32_16x16x32_bf16 v[20:23], v[166:169], v[182:185], v[20:23]
	v_mfma_f32_16x16x32_bf16 v[16:19], v[166:169], v[186:189], v[16:19]
	v_mfma_f32_16x16x32_bf16 v[8:11], v[166:169], v[190:193], v[8:11]
	v_mfma_f32_16x16x32_bf16 v[4:7], v[170:173], v[174:177], v[4:7]
	v_mfma_f32_16x16x32_bf16 v[0:3], v[170:173], v[182:185], v[0:3]
	v_mfma_f32_16x16x32_bf16 v[24:27], v[170:173], v[186:189], v[24:27]
	v_mfma_f32_16x16x32_bf16 v[12:15], v[170:173], v[190:193], v[12:15]
	ds_read_b128 v[158:161], v213 offset:8192
	ds_read_b128 v[162:165], v213 offset:10240
	ds_read_b128 v[166:169], v213 offset:12288
	ds_read_b128 v[170:173], v213 offset:14336
	s_waitcnt lgkmcnt(4)
	v_mfma_f32_16x16x32_bf16 v[124:127], v[142:145], v[194:197], v[124:127]
	v_mfma_f32_16x16x32_bf16 v[120:123], v[142:145], v[198:201], v[120:123]
	v_mfma_f32_16x16x32_bf16 v[116:119], v[142:145], v[202:205], v[116:119]
	v_mfma_f32_16x16x32_bf16 v[112:115], v[142:145], v[206:209], v[112:115]
	v_mfma_f32_16x16x32_bf16 v[108:111], v[146:149], v[194:197], v[108:111]
	v_mfma_f32_16x16x32_bf16 v[104:107], v[146:149], v[198:201], v[104:107]
	v_mfma_f32_16x16x32_bf16 v[100:103], v[146:149], v[202:205], v[100:103]
	v_mfma_f32_16x16x32_bf16 v[96:99], v[146:149], v[206:209], v[96:99]
	v_mfma_f32_16x16x32_bf16 v[92:95], v[150:153], v[194:197], v[92:95]
	v_mfma_f32_16x16x32_bf16 v[88:91], v[150:153], v[198:201], v[88:91]
	v_mfma_f32_16x16x32_bf16 v[84:87], v[150:153], v[202:205], v[84:87]
	v_mfma_f32_16x16x32_bf16 v[80:83], v[150:153], v[206:209], v[80:83]
	v_mfma_f32_16x16x32_bf16 v[76:79], v[154:157], v[194:197], v[76:79]
	v_mfma_f32_16x16x32_bf16 v[72:75], v[154:157], v[198:201], v[72:75]
	v_mfma_f32_16x16x32_bf16 v[68:71], v[154:157], v[202:205], v[68:71]
	v_mfma_f32_16x16x32_bf16 v[64:67], v[154:157], v[206:209], v[64:67]
	s_add_u32 s50, s50, 0x80
	s_addc_u32 s51, s51, 0
	s_add_i32 s49, s49, 1
	s_branch .Lg1_top

.Lg2_top:
	s_xor_b32 s62, s62, 0x10000
	s_mov_b32 m0, s62
	s_add_u32 s50, s48, s12
	s_addc_u32 s51, s49, s13
	s_waitcnt lgkmcnt(0)
	s_waitcnt vmcnt(0)
	s_barrier
	global_load_lds_dwordx4 v178, s[50:51]
	ds_read_b128 v[146:149], v180
	ds_read_b128 v[150:153], v180 offset:2048
	ds_read_b128 v[154:157], v180 offset:4096
	ds_read_b128 v[158:161], v180 offset:6144
	ds_read_b128 v[182:185], v215 offset:32768
	ds_read_b128 v[186:189], v215 offset:34816
	ds_read_b128 v[190:193], v215 offset:36864
	ds_read_b128 v[194:197], v215 offset:38912
	v_mfma_f32_16x16x32_bf16 v[60:63], v[162:165], v[198:201], v[60:63]
	v_mfma_f32_16x16x32_bf16 v[56:59], v[162:165], v[202:205], v[56:59]
	s_add_u32 m0, s62, 0x2000
	s_add_u32 s50, s48, s14
	s_addc_u32 s51, s49, s15
	global_load_lds_dwordx4 v178, s[50:51]
	v_mfma_f32_16x16x32_bf16 v[52:55], v[162:165], v[206:209], v[52:55]
	v_mfma_f32_16x16x32_bf16 v[44:47], v[162:165], v[210:213], v[44:47]
	s_add_u32 m0, s62, 0x4000
	s_add_u32 s50, s48, s16
	s_addc_u32 s51, s49, s17
	global_load_lds_dwordx4 v178, s[50:51]
	v_mfma_f32_16x16x32_bf16 v[36:39], v[166:169], v[198:201], v[36:39]
	v_mfma_f32_16x16x32_bf16 v[32:35], v[166:169], v[202:205], v[32:35]
	s_add_u32 m0, s62, 0x6000
	s_add_u32 s50, s48, s18
	s_addc_u32 s51, s49, s19
	global_load_lds_dwordx4 v178, s[50:51]
	v_mfma_f32_16x16x32_bf16 v[28:31], v[166:169], v[206:209], v[28:31]
	v_mfma_f32_16x16x32_bf16 v[24:27], v[166:169], v[210:213], v[24:27]
	s_add_u32 m0, s62, 0x8000
	s_add_u32 s50, s48, s22
	s_addc_u32 s51, s49, s23
	global_load_lds_dwordx4 v179, s[50:51]
	v_mfma_f32_16x16x32_bf16 v[20:23], v[170:173], v[198:201], v[20:23]
	v_mfma_f32_16x16x32_bf16 v[16:19], v[170:173], v[202:205], v[16:19]
	s_add_u32 m0, s62, 0xa000
	s_add_u32 s50, s48, s36
	s_addc_u32 s51, s49, s37
	global_load_lds_dwordx4 v179, s[50:51]
	v_mfma_f32_16x16x32_bf16 v[12:15], v[170:173], v[206:209], v[12:15]
	v_mfma_f32_16x16x32_bf16 v[8:11], v[170:173], v[210:213], v[8:11]
	s_add_u32 m0, s62, 0xc000
	s_add_u32 s50, s48, s40
	s_addc_u32 s51, s49, s41
	global_load_lds_dwordx4 v179, s[50:51]
	v_mfma_f32_16x16x32_bf16 v[4:7], v[174:177], v[198:201], v[4:7]
	v_mfma_f32_16x16x32_bf16 v[0:3], v[174:177], v[202:205], v[0:3]
	s_add_u32 m0, s62, 0xe000
	s_add_u32 s50, s48, s42
	s_addc_u32 s51, s49, s43
	global_load_lds_dwordx4 v179, s[50:51]
	v_mfma_f32_16x16x32_bf16 v[48:51], v[174:177], v[206:209], v[48:51]
	v_mfma_f32_16x16x32_bf16 v[40:43], v[174:177], v[210:213], v[40:43]
.Lg2_entry:
	ds_read_b128 v[162:165], v180 offset:8192
	ds_read_b128 v[166:169], v180 offset:10240
	ds_read_b128 v[170:173], v180 offset:12288
	ds_read_b128 v[174:177], v180 offset:14336
	s_waitcnt lgkmcnt(4)
	v_mfma_f32_16x16x32_bf16 v[124:127], v[146:149], v[182:185], v[124:127]
	v_mfma_f32_16x16x32_bf16 v[120:123], v[146:149], v[186:189], v[120:123]
	v_mfma_f32_16x16x32_bf16 v[116:119], v[146:149], v[190:193], v[116:119]
	v_mfma_f32_16x16x32_bf16 v[112:115], v[146:149], v[194:197], v[112:115]
	v_mfma_f32_16x16x32_bf16 v[108:111], v[150:153], v[182:185], v[108:111]
	v_mfma_f32_16x16x32_bf16 v[104:107], v[150:153], v[186:189], v[104:107]
	v_mfma_f32_16x16x32_bf16 v[100:103], v[150:153], v[190:193], v[100:103]
	v_mfma_f32_16x16x32_bf16 v[96:99], v[150:153], v[194:197], v[96:99]
	v_mfma_f32_16x16x32_bf16 v[92:95], v[154:157], v[182:185], v[92:95]
	v_mfma_f32_16x16x32_bf16 v[88:91], v[154:157], v[186:189], v[88:91]
	v_mfma_f32_16x16x32_bf16 v[84:87], v[154:157], v[190:193], v[84:87]
	v_mfma_f32_16x16x32_bf16 v[80:83], v[154:157], v[194:197], v[80:83]
	v_mfma_f32_16x16x32_bf16 v[76:79], v[158:161], v[182:185], v[76:79]
	v_mfma_f32_16x16x32_bf16 v[72:75], v[158:161], v[186:189], v[72:75]
	v_mfma_f32_16x16x32_bf16 v[68:71], v[158:161], v[190:193], v[68:71]
	v_mfma_f32_16x16x32_bf16 v[64:67], v[158:161], v[194:197], v[64:67]
	ds_read_b128 v[146:149], v214
	ds_read_b128 v[150:153], v214 offset:2048
	ds_read_b128 v[154:157], v214 offset:4096
	ds_read_b128 v[158:161], v214 offset:6144
	ds_read_b128 v[198:201], v216 offset:32768
	ds_read_b128 v[202:205], v216 offset:34816
	ds_read_b128 v[206:209], v216 offset:36864
	ds_read_b128 v[210:213], v216 offset:38912
	s_waitcnt lgkmcnt(8)
	v_mfma_f32_16x16x32_bf16 v[60:63], v[162:165], v[182:185], v[60:63]
	v_mfma_f32_16x16x32_bf16 v[56:59], v[162:165], v[186:189], v[56:59]
	v_mfma_f32_16x16x32_bf16 v[52:55], v[162:165], v[190:193], v[52:55]
	v_mfma_f32_16x16x32_bf16 v[44:47], v[162:165], v[194:197], v[44:47]
	v_mfma_f32_16x16x32_bf16 v[36:39], v[166:169], v[182:185], v[36:39]
	v_mfma_f32_16x16x32_bf16 v[32:35], v[166:169], v[186:189], v[32:35]
	v_mfma_f32_16x16x32_bf16 v[28:31], v[166:169], v[190:193], v[28:31]
	v_mfma_f32_16x16x32_bf16 v[24:27], v[166:169], v[194:197], v[24:27]
	v_mfma_f32_16x16x32_bf16 v[20:23], v[170:173], v[182:185], v[20:23]
	v_mfma_f32_16x16x32_bf16 v[16:19], v[170:173], v[186:189], v[16:19]
	v_mfma_f32_16x16x32_bf16 v[12:15], v[170:173], v[190:193], v[12:15]
	v_mfma_f32_16x16x32_bf16 v[8:11], v[170:173], v[194:197], v[8:11]
	v_mfma_f32_16x16x32_bf16 v[4:7], v[174:177], v[182:185], v[4:7]
	v_mfma_f32_16x16x32_bf16 v[0:3], v[174:177], v[186:189], v[0:3]
	v_mfma_f32_16x16x32_bf16 v[48:51], v[174:177], v[190:193], v[48:51]
	v_mfma_f32_16x16x32_bf16 v[40:43], v[174:177], v[194:197], v[40:43]
	ds_read_b128 v[162:165], v214 offset:8192
	ds_read_b128 v[166:169], v214 offset:10240
	ds_read_b128 v[170:173], v214 offset:12288
	ds_read_b128 v[174:177], v214 offset:14336
	s_waitcnt lgkmcnt(4)
	v_mfma_f32_16x16x32_bf16 v[124:127], v[146:149], v[198:201], v[124:127]
	v_mfma_f32_16x16x32_bf16 v[120:123], v[146:149], v[202:205], v[120:123]
	v_mfma_f32_16x16x32_bf16 v[116:119], v[146:149], v[206:209], v[116:119]
	v_mfma_f32_16x16x32_bf16 v[112:115], v[146:149], v[210:213], v[112:115]
	v_mfma_f32_16x16x32_bf16 v[108:111], v[150:153], v[198:201], v[108:111]
	v_mfma_f32_16x16x32_bf16 v[104:107], v[150:153], v[202:205], v[104:107]
	v_mfma_f32_16x16x32_bf16 v[100:103], v[150:153], v[206:209], v[100:103]
	v_mfma_f32_16x16x32_bf16 v[96:99], v[150:153], v[210:213], v[96:99]
	v_mfma_f32_16x16x32_bf16 v[92:95], v[154:157], v[198:201], v[92:95]
	v_mfma_f32_16x16x32_bf16 v[88:91], v[154:157], v[202:205], v[88:91]
	v_mfma_f32_16x16x32_bf16 v[84:87], v[154:157], v[206:209], v[84:87]
	v_mfma_f32_16x16x32_bf16 v[80:83], v[154:157], v[210:213], v[80:83]
	v_mfma_f32_16x16x32_bf16 v[76:79], v[158:161], v[198:201], v[76:79]
	v_mfma_f32_16x16x32_bf16 v[72:75], v[158:161], v[202:205], v[72:75]
	v_mfma_f32_16x16x32_bf16 v[68:71], v[158:161], v[206:209], v[68:71]
	v_mfma_f32_16x16x32_bf16 v[64:67], v[158:161], v[210:213], v[64:67]
	s_add_u32 s48, s48, 0x80
	s_addc_u32 s49, s49, 0
	s_add_i32 s47, s47, 1
	s_cmp_lt_u32 s47, 15
	s_cbranch_scc0 .Lg2_last
	s_xor_b32 s62, s62, 0x10000
	s_mov_b32 m0, s62
	s_add_u32 s50, s48, s12
	s_addc_u32 s51, s49, s13
	s_waitcnt lgkmcnt(0)
	s_waitcnt vmcnt(0)
	s_barrier
	global_load_lds_dwordx4 v178, s[50:51]
	ds_read_b128 v[146:149], v217
	ds_read_b128 v[150:153], v217 offset:2048
	ds_read_b128 v[154:157], v217 offset:4096
	ds_read_b128 v[158:161], v217 offset:6144
	ds_read_b128 v[182:185], v219 offset:32768
	ds_read_b128 v[186:189], v219 offset:34816
	ds_read_b128 v[190:193], v219 offset:36864
	ds_read_b128 v[194:197], v219 offset:38912
	v_mfma_f32_16x16x32_bf16 v[60:63], v[162:165], v[198:201], v[60:63]
	v_mfma_f32_16x16x32_bf16 v[56:59], v[162:165], v[202:205], v[56:59]
	s_add_u32 m0, s62, 0x2000
	s_add_u32 s50, s48, s14
	s_addc_u32 s51, s49, s15
	global_load_lds_dwordx4 v178, s[50:51]
	v_mfma_f32_16x16x32_bf16 v[52:55], v[162:165], v[206:209], v[52:55]
	v_mfma_f32_16x16x32_bf16 v[44:47], v[162:165], v[210:213], v[44:47]
	s_add_u32 m0, s62, 0x4000
	s_add_u32 s50, s48, s16
	s_addc_u32 s51, s49, s17
	global_load_lds_dwordx4 v178, s[50:51]
	v_mfma_f32_16x16x32_bf16 v[36:39], v[166:169], v[198:201], v[36:39]
	v_mfma_f32_16x16x32_bf16 v[32:35], v[166:169], v[202:205], v[32:35]
	s_add_u32 m0, s62, 0x6000
	s_add_u32 s50, s48, s18
	s_addc_u32 s51, s49, s19
	global_load_lds_dwordx4 v178, s[50:51]
	v_mfma_f32_16x16x32_bf16 v[28:31], v[166:169], v[206:209], v[28:31]
	v_mfma_f32_16x16x32_bf16 v[24:27], v[166:169], v[210:213], v[24:27]
	s_add_u32 m0, s62, 0x8000
	s_add_u32 s50, s48, s22
	s_addc_u32 s51, s49, s23
	global_load_lds_dwordx4 v179, s[50:51]
	v_mfma_f32_16x16x32_bf16 v[20:23], v[170:173], v[198:201], v[20:23]
	v_mfma_f32_16x16x32_bf16 v[16:19], v[170:173], v[202:205], v[16:19]
	s_add_u32 m0, s62, 0xa000
	s_add_u32 s50, s48, s36
	s_addc_u32 s51, s49, s37
	global_load_lds_dwordx4 v179, s[50:51]
	v_mfma_f32_16x16x32_bf16 v[12:15], v[170:173], v[206:209], v[12:15]
	v_mfma_f32_16x16x32_bf16 v[8:11], v[170:173], v[210:213], v[8:11]
	s_add_u32 m0, s62, 0xc000
	s_add_u32 s50, s48, s40
	s_addc_u32 s51, s49, s41
	global_load_lds_dwordx4 v179, s[50:51]
	v_mfma_f32_16x16x32_bf16 v[4:7], v[174:177], v[198:201], v[4:7]
	v_mfma_f32_16x16x32_bf16 v[0:3], v[174:177], v[202:205], v[0:3]
	s_add_u32 m0, s62, 0xe000
	s_add_u32 s50, s48, s42
	s_addc_u32 s51, s49, s43
	global_load_lds_dwordx4 v179, s[50:51]
	v_mfma_f32_16x16x32_bf16 v[48:51], v[174:177], v[206:209], v[48:51]
	v_mfma_f32_16x16x32_bf16 v[40:43], v[174:177], v[210:213], v[40:43]
	ds_read_b128 v[162:165], v217 offset:8192
	ds_read_b128 v[166:169], v217 offset:10240
	ds_read_b128 v[170:173], v217 offset:12288
	ds_read_b128 v[174:177], v217 offset:14336
	s_waitcnt lgkmcnt(4)
	v_mfma_f32_16x16x32_bf16 v[124:127], v[146:149], v[182:185], v[124:127]
	v_mfma_f32_16x16x32_bf16 v[120:123], v[146:149], v[186:189], v[120:123]
	v_mfma_f32_16x16x32_bf16 v[116:119], v[146:149], v[190:193], v[116:119]
	v_mfma_f32_16x16x32_bf16 v[112:115], v[146:149], v[194:197], v[112:115]
	v_mfma_f32_16x16x32_bf16 v[108:111], v[150:153], v[182:185], v[108:111]
	v_mfma_f32_16x16x32_bf16 v[104:107], v[150:153], v[186:189], v[104:107]
	v_mfma_f32_16x16x32_bf16 v[100:103], v[150:153], v[190:193], v[100:103]
	v_mfma_f32_16x16x32_bf16 v[96:99], v[150:153], v[194:197], v[96:99]
	v_mfma_f32_16x16x32_bf16 v[92:95], v[154:157], v[182:185], v[92:95]
	v_mfma_f32_16x16x32_bf16 v[88:91], v[154:157], v[186:189], v[88:91]
	v_mfma_f32_16x16x32_bf16 v[84:87], v[154:157], v[190:193], v[84:87]
	v_mfma_f32_16x16x32_bf16 v[80:83], v[154:157], v[194:197], v[80:83]
	v_mfma_f32_16x16x32_bf16 v[76:79], v[158:161], v[182:185], v[76:79]
	v_mfma_f32_16x16x32_bf16 v[72:75], v[158:161], v[186:189], v[72:75]
	v_mfma_f32_16x16x32_bf16 v[68:71], v[158:161], v[190:193], v[68:71]
	v_mfma_f32_16x16x32_bf16 v[64:67], v[158:161], v[194:197], v[64:67]
	ds_read_b128 v[146:149], v218
	ds_read_b128 v[150:153], v218 offset:2048
	ds_read_b128 v[154:157], v218 offset:4096
	ds_read_b128 v[158:161], v218 offset:6144
	ds_read_b128 v[198:201], v220 offset:32768
	ds_read_b128 v[202:205], v220 offset:34816
	ds_read_b128 v[206:209], v220 offset:36864
	ds_read_b128 v[210:213], v220 offset:38912
	s_waitcnt lgkmcnt(8)
	v_mfma_f32_16x16x32_bf16 v[60:63], v[162:165], v[182:185], v[60:63]
	v_mfma_f32_16x16x32_bf16 v[56:59], v[162:165], v[186:189], v[56:59]
	v_mfma_f32_16x16x32_bf16 v[52:55], v[162:165], v[190:193], v[52:55]
	v_mfma_f32_16x16x32_bf16 v[44:47], v[162:165], v[194:197], v[44:47]
	v_mfma_f32_16x16x32_bf16 v[36:39], v[166:169], v[182:185], v[36:39]
	v_mfma_f32_16x16x32_bf16 v[32:35], v[166:169], v[186:189], v[32:35]
	v_mfma_f32_16x16x32_bf16 v[28:31], v[166:169], v[190:193], v[28:31]
	v_mfma_f32_16x16x32_bf16 v[24:27], v[166:169], v[194:197], v[24:27]
	v_mfma_f32_16x16x32_bf16 v[20:23], v[170:173], v[182:185], v[20:23]
	v_mfma_f32_16x16x32_bf16 v[16:19], v[170:173], v[186:189], v[16:19]
	v_mfma_f32_16x16x32_bf16 v[12:15], v[170:173], v[190:193], v[12:15]
	v_mfma_f32_16x16x32_bf16 v[8:11], v[170:173], v[194:197], v[8:11]
	v_mfma_f32_16x16x32_bf16 v[4:7], v[174:177], v[182:185], v[4:7]
	v_mfma_f32_16x16x32_bf16 v[0:3], v[174:177], v[186:189], v[0:3]
	v_mfma_f32_16x16x32_bf16 v[48:51], v[174:177], v[190:193], v[48:51]
	v_mfma_f32_16x16x32_bf16 v[40:43], v[174:177], v[194:197], v[40:43]
	ds_read_b128 v[162:165], v218 offset:8192
	ds_read_b128 v[166:169], v218 offset:10240
	ds_read_b128 v[170:173], v218 offset:12288
	ds_read_b128 v[174:177], v218 offset:14336
	s_waitcnt lgkmcnt(4)
	v_mfma_f32_16x16x32_bf16 v[124:127], v[146:149], v[198:201], v[124:127]
	v_mfma_f32_16x16x32_bf16 v[120:123], v[146:149], v[202:205], v[120:123]
	v_mfma_f32_16x16x32_bf16 v[116:119], v[146:149], v[206:209], v[116:119]
	v_mfma_f32_16x16x32_bf16 v[112:115], v[146:149], v[210:213], v[112:115]
	v_mfma_f32_16x16x32_bf16 v[108:111], v[150:153], v[198:201], v[108:111]
	v_mfma_f32_16x16x32_bf16 v[104:107], v[150:153], v[202:205], v[104:107]
	v_mfma_f32_16x16x32_bf16 v[100:103], v[150:153], v[206:209], v[100:103]
	v_mfma_f32_16x16x32_bf16 v[96:99], v[150:153], v[210:213], v[96:99]
	v_mfma_f32_16x16x32_bf16 v[92:95], v[154:157], v[198:201], v[92:95]
	v_mfma_f32_16x16x32_bf16 v[88:91], v[154:157], v[202:205], v[88:91]
	v_mfma_f32_16x16x32_bf16 v[84:87], v[154:157], v[206:209], v[84:87]
	v_mfma_f32_16x16x32_bf16 v[80:83], v[154:157], v[210:213], v[80:83]
	v_mfma_f32_16x16x32_bf16 v[76:79], v[158:161], v[198:201], v[76:79]
	v_mfma_f32_16x16x32_bf16 v[72:75], v[158:161], v[202:205], v[72:75]
	v_mfma_f32_16x16x32_bf16 v[68:71], v[158:161], v[206:209], v[68:71]
	v_mfma_f32_16x16x32_bf16 v[64:67], v[158:161], v[210:213], v[64:67]
	s_add_u32 s48, s48, 0x80
	s_addc_u32 s49, s49, 0
	s_add_i32 s47, s47, 1
	s_branch .Lg2_top

.Lg5_top:
	s_xor_b32 s87, s87, 0x10000
	s_mov_b32 m0, s87
	s_add_u32 s70, s68, 0x4000080
	s_addc_u32 s71, s69, 0
	s_waitcnt lgkmcnt(0)
	s_waitcnt vmcnt(0)
	s_barrier
	global_load_lds_dwordx4 v242, s[70:71]
	ds_read_b128 v[176:179], v180
	ds_read_b128 v[182:185], v180 offset:2048
	ds_read_b128 v[186:189], v180 offset:4096
	ds_read_b128 v[190:193], v180 offset:6144
	ds_read_b128 v[210:213], v245 offset:32768
	ds_read_b128 v[214:217], v245 offset:34816
	ds_read_b128 v[218:221], v245 offset:36864
	ds_read_b128 v[222:225], v245 offset:38912
	v_mfma_f32_16x16x32_bf16 v[60:63], v[194:197], v[226:229], v[60:63]
	v_mfma_f32_16x16x32_bf16 v[56:59], v[194:197], v[230:233], v[56:59]
	s_add_u32 m0, s87, 0x2000
	s_add_u32 s70, s68, 0x4020080
	s_addc_u32 s71, s69, 0
	global_load_lds_dwordx4 v242, s[70:71]
	v_mfma_f32_16x16x32_bf16 v[52:55], v[194:197], v[234:237], v[52:55]
	v_mfma_f32_16x16x32_bf16 v[48:51], v[194:197], v[238:241], v[48:51]
	s_add_u32 m0, s87, 0x4000
	s_add_u32 s70, s68, 0x4040080
	s_addc_u32 s71, s69, 0
	global_load_lds_dwordx4 v242, s[70:71]
	v_mfma_f32_16x16x32_bf16 v[44:47], v[198:201], v[226:229], v[44:47]
	v_mfma_f32_16x16x32_bf16 v[40:43], v[198:201], v[230:233], v[40:43]
	s_add_u32 m0, s87, 0x6000
	s_add_u32 s70, s68, s14
	s_addc_u32 s71, s69, s15
	global_load_lds_dwordx4 v242, s[70:71]
	v_mfma_f32_16x16x32_bf16 v[36:39], v[198:201], v[234:237], v[36:39]
	v_mfma_f32_16x16x32_bf16 v[32:35], v[198:201], v[238:241], v[32:35]
	s_add_u32 m0, s87, 0x8000
	s_add_u32 s70, s68, s16
	s_addc_u32 s71, s69, s17
	global_load_lds_dwordx4 v243, s[70:71]
	v_mfma_f32_16x16x32_bf16 v[28:31], v[202:205], v[226:229], v[28:31]
	v_mfma_f32_16x16x32_bf16 v[24:27], v[202:205], v[230:233], v[24:27]
	s_add_u32 m0, s87, 0xa000
	s_add_u32 s70, s68, s18
	s_addc_u32 s71, s69, s19
	global_load_lds_dwordx4 v243, s[70:71]
	v_mfma_f32_16x16x32_bf16 v[20:23], v[202:205], v[234:237], v[20:23]
	v_mfma_f32_16x16x32_bf16 v[16:19], v[202:205], v[238:241], v[16:19]
	s_add_u32 m0, s87, 0xc000
	s_add_u32 s70, s68, s22
	s_addc_u32 s71, s69, s23
	global_load_lds_dwordx4 v243, s[70:71]
	v_mfma_f32_16x16x32_bf16 v[8:11], v[206:209], v[226:229], v[8:11]
	v_mfma_f32_16x16x32_bf16 v[0:3], v[206:209], v[230:233], v[0:3]
	s_add_u32 m0, s87, 0xe000
	s_add_u32 s70, s68, s36
	s_addc_u32 s71, s69, s37
	global_load_lds_dwordx4 v243, s[70:71]
	v_mfma_f32_16x16x32_bf16 v[12:15], v[206:209], v[234:237], v[12:15]
	v_mfma_f32_16x16x32_bf16 v[4:7], v[206:209], v[238:241], v[4:7]
.Lg5_entry:
	ds_read_b128 v[194:197], v180 offset:8192
	ds_read_b128 v[198:201], v180 offset:10240
	ds_read_b128 v[202:205], v180 offset:12288
	ds_read_b128 v[206:209], v180 offset:14336
	s_waitcnt lgkmcnt(4)
	v_mfma_f32_16x16x32_bf16 v[124:127], v[176:179], v[210:213], v[124:127]
	v_mfma_f32_16x16x32_bf16 v[120:123], v[176:179], v[214:217], v[120:123]
	v_mfma_f32_16x16x32_bf16 v[116:119], v[176:179], v[218:221], v[116:119]
	v_mfma_f32_16x16x32_bf16 v[112:115], v[176:179], v[222:225], v[112:115]
	v_mfma_f32_16x16x32_bf16 v[108:111], v[182:185], v[210:213], v[108:111]
	v_mfma_f32_16x16x32_bf16 v[104:107], v[182:185], v[214:217], v[104:107]
	v_mfma_f32_16x16x32_bf16 v[100:103], v[182:185], v[218:221], v[100:103]
	v_mfma_f32_16x16x32_bf16 v[96:99], v[182:185], v[222:225], v[96:99]
	v_mfma_f32_16x16x32_bf16 v[92:95], v[186:189], v[210:213], v[92:95]
	v_mfma_f32_16x16x32_bf16 v[88:91], v[186:189], v[214:217], v[88:91]
	v_mfma_f32_16x16x32_bf16 v[84:87], v[186:189], v[218:221], v[84:87]
	v_mfma_f32_16x16x32_bf16 v[80:83], v[186:189], v[222:225], v[80:83]
	v_mfma_f32_16x16x32_bf16 v[76:79], v[190:193], v[210:213], v[76:79]
	v_mfma_f32_16x16x32_bf16 v[72:75], v[190:193], v[214:217], v[72:75]
	v_mfma_f32_16x16x32_bf16 v[68:71], v[190:193], v[218:221], v[68:71]
	v_mfma_f32_16x16x32_bf16 v[64:67], v[190:193], v[222:225], v[64:67]
	ds_read_b128 v[176:179], v244
	ds_read_b128 v[182:185], v244 offset:2048
	ds_read_b128 v[186:189], v244 offset:4096
	ds_read_b128 v[190:193], v244 offset:6144
	ds_read_b128 v[226:229], v246 offset:32768
	ds_read_b128 v[230:233], v246 offset:34816
	ds_read_b128 v[234:237], v246 offset:36864
	ds_read_b128 v[238:241], v246 offset:38912
	s_waitcnt lgkmcnt(8)
	v_mfma_f32_16x16x32_bf16 v[60:63], v[194:197], v[210:213], v[60:63]
	v_mfma_f32_16x16x32_bf16 v[56:59], v[194:197], v[214:217], v[56:59]
	v_mfma_f32_16x16x32_bf16 v[52:55], v[194:197], v[218:221], v[52:55]
	v_mfma_f32_16x16x32_bf16 v[48:51], v[194:197], v[222:225], v[48:51]
	v_mfma_f32_16x16x32_bf16 v[44:47], v[198:201], v[210:213], v[44:47]
	v_mfma_f32_16x16x32_bf16 v[40:43], v[198:201], v[214:217], v[40:43]
	v_mfma_f32_16x16x32_bf16 v[36:39], v[198:201], v[218:221], v[36:39]
	v_mfma_f32_16x16x32_bf16 v[32:35], v[198:201], v[222:225], v[32:35]
	v_mfma_f32_16x16x32_bf16 v[28:31], v[202:205], v[210:213], v[28:31]
	v_mfma_f32_16x16x32_bf16 v[24:27], v[202:205], v[214:217], v[24:27]
	v_mfma_f32_16x16x32_bf16 v[20:23], v[202:205], v[218:221], v[20:23]
	v_mfma_f32_16x16x32_bf16 v[16:19], v[202:205], v[222:225], v[16:19]
	v_mfma_f32_16x16x32_bf16 v[8:11], v[206:209], v[210:213], v[8:11]
	v_mfma_f32_16x16x32_bf16 v[0:3], v[206:209], v[214:217], v[0:3]
	v_mfma_f32_16x16x32_bf16 v[12:15], v[206:209], v[218:221], v[12:15]
	v_mfma_f32_16x16x32_bf16 v[4:7], v[206:209], v[222:225], v[4:7]
	ds_read_b128 v[194:197], v244 offset:8192
	ds_read_b128 v[198:201], v244 offset:10240
	ds_read_b128 v[202:205], v244 offset:12288
	ds_read_b128 v[206:209], v244 offset:14336
	s_waitcnt lgkmcnt(4)
	v_mfma_f32_16x16x32_bf16 v[124:127], v[176:179], v[226:229], v[124:127]
	v_mfma_f32_16x16x32_bf16 v[120:123], v[176:179], v[230:233], v[120:123]
	v_mfma_f32_16x16x32_bf16 v[116:119], v[176:179], v[234:237], v[116:119]
	v_mfma_f32_16x16x32_bf16 v[112:115], v[176:179], v[238:241], v[112:115]
	v_mfma_f32_16x16x32_bf16 v[108:111], v[182:185], v[226:229], v[108:111]
	v_mfma_f32_16x16x32_bf16 v[104:107], v[182:185], v[230:233], v[104:107]
	v_mfma_f32_16x16x32_bf16 v[100:103], v[182:185], v[234:237], v[100:103]
	v_mfma_f32_16x16x32_bf16 v[96:99], v[182:185], v[238:241], v[96:99]
	v_mfma_f32_16x16x32_bf16 v[92:95], v[186:189], v[226:229], v[92:95]
	v_mfma_f32_16x16x32_bf16 v[88:91], v[186:189], v[230:233], v[88:91]
	v_mfma_f32_16x16x32_bf16 v[84:87], v[186:189], v[234:237], v[84:87]
	v_mfma_f32_16x16x32_bf16 v[80:83], v[186:189], v[238:241], v[80:83]
	v_mfma_f32_16x16x32_bf16 v[76:79], v[190:193], v[226:229], v[76:79]
	v_mfma_f32_16x16x32_bf16 v[72:75], v[190:193], v[230:233], v[72:75]
	v_mfma_f32_16x16x32_bf16 v[68:71], v[190:193], v[234:237], v[68:71]
	v_mfma_f32_16x16x32_bf16 v[64:67], v[190:193], v[238:241], v[64:67]
	s_add_u32 s68, s68, 0x80
	s_addc_u32 s69, s69, 0
	s_add_i32 s86, s86, 1
	s_cmp_lt_u32 s86, 15
	s_cbranch_scc0 .Lg5_last
	s_xor_b32 s87, s87, 0x10000
	s_mov_b32 m0, s87
	s_add_u32 s70, s68, 0x4000080
	s_addc_u32 s71, s69, 0
	s_waitcnt lgkmcnt(0)
	s_waitcnt vmcnt(0)
	s_barrier
	global_load_lds_dwordx4 v242, s[70:71]
	ds_read_b128 v[176:179], v247
	ds_read_b128 v[182:185], v247 offset:2048
	ds_read_b128 v[186:189], v247 offset:4096
	ds_read_b128 v[190:193], v247 offset:6144
	ds_read_b128 v[210:213], v249 offset:32768
	ds_read_b128 v[214:217], v249 offset:34816
	ds_read_b128 v[218:221], v249 offset:36864
	ds_read_b128 v[222:225], v249 offset:38912
	v_mfma_f32_16x16x32_bf16 v[60:63], v[194:197], v[226:229], v[60:63]
	v_mfma_f32_16x16x32_bf16 v[56:59], v[194:197], v[230:233], v[56:59]
	s_add_u32 m0, s87, 0x2000
	s_add_u32 s70, s68, 0x4020080
	s_addc_u32 s71, s69, 0
	global_load_lds_dwordx4 v242, s[70:71]
	v_mfma_f32_16x16x32_bf16 v[52:55], v[194:197], v[234:237], v[52:55]
	v_mfma_f32_16x16x32_bf16 v[48:51], v[194:197], v[238:241], v[48:51]
	s_add_u32 m0, s87, 0x4000
	s_add_u32 s70, s68, 0x4040080
	s_addc_u32 s71, s69, 0
	global_load_lds_dwordx4 v242, s[70:71]
	v_mfma_f32_16x16x32_bf16 v[44:47], v[198:201], v[226:229], v[44:47]
	v_mfma_f32_16x16x32_bf16 v[40:43], v[198:201], v[230:233], v[40:43]
	s_add_u32 m0, s87, 0x6000
	s_add_u32 s70, s68, s14
	s_addc_u32 s71, s69, s15
	global_load_lds_dwordx4 v242, s[70:71]
	v_mfma_f32_16x16x32_bf16 v[36:39], v[198:201], v[234:237], v[36:39]
	v_mfma_f32_16x16x32_bf16 v[32:35], v[198:201], v[238:241], v[32:35]
	s_add_u32 m0, s87, 0x8000
	s_add_u32 s70, s68, s16
	s_addc_u32 s71, s69, s17
	global_load_lds_dwordx4 v243, s[70:71]
	v_mfma_f32_16x16x32_bf16 v[28:31], v[202:205], v[226:229], v[28:31]
	v_mfma_f32_16x16x32_bf16 v[24:27], v[202:205], v[230:233], v[24:27]
	s_add_u32 m0, s87, 0xa000
	s_add_u32 s70, s68, s18
	s_addc_u32 s71, s69, s19
	global_load_lds_dwordx4 v243, s[70:71]
	v_mfma_f32_16x16x32_bf16 v[20:23], v[202:205], v[234:237], v[20:23]
	v_mfma_f32_16x16x32_bf16 v[16:19], v[202:205], v[238:241], v[16:19]
	s_add_u32 m0, s87, 0xc000
	s_add_u32 s70, s68, s22
	s_addc_u32 s71, s69, s23
	global_load_lds_dwordx4 v243, s[70:71]
	v_mfma_f32_16x16x32_bf16 v[8:11], v[206:209], v[226:229], v[8:11]
	v_mfma_f32_16x16x32_bf16 v[0:3], v[206:209], v[230:233], v[0:3]
	s_add_u32 m0, s87, 0xe000
	s_add_u32 s70, s68, s36
	s_addc_u32 s71, s69, s37
	global_load_lds_dwordx4 v243, s[70:71]
	v_mfma_f32_16x16x32_bf16 v[12:15], v[206:209], v[234:237], v[12:15]
	v_mfma_f32_16x16x32_bf16 v[4:7], v[206:209], v[238:241], v[4:7]
	ds_read_b128 v[194:197], v247 offset:8192
	ds_read_b128 v[198:201], v247 offset:10240
	ds_read_b128 v[202:205], v247 offset:12288
	ds_read_b128 v[206:209], v247 offset:14336
	s_waitcnt lgkmcnt(4)
	v_mfma_f32_16x16x32_bf16 v[124:127], v[176:179], v[210:213], v[124:127]
	v_mfma_f32_16x16x32_bf16 v[120:123], v[176:179], v[214:217], v[120:123]
	v_mfma_f32_16x16x32_bf16 v[116:119], v[176:179], v[218:221], v[116:119]
	v_mfma_f32_16x16x32_bf16 v[112:115], v[176:179], v[222:225], v[112:115]
	v_mfma_f32_16x16x32_bf16 v[108:111], v[182:185], v[210:213], v[108:111]
	v_mfma_f32_16x16x32_bf16 v[104:107], v[182:185], v[214:217], v[104:107]
	v_mfma_f32_16x16x32_bf16 v[100:103], v[182:185], v[218:221], v[100:103]
	v_mfma_f32_16x16x32_bf16 v[96:99], v[182:185], v[222:225], v[96:99]
	v_mfma_f32_16x16x32_bf16 v[92:95], v[186:189], v[210:213], v[92:95]
	v_mfma_f32_16x16x32_bf16 v[88:91], v[186:189], v[214:217], v[88:91]
	v_mfma_f32_16x16x32_bf16 v[84:87], v[186:189], v[218:221], v[84:87]
	v_mfma_f32_16x16x32_bf16 v[80:83], v[186:189], v[222:225], v[80:83]
	v_mfma_f32_16x16x32_bf16 v[76:79], v[190:193], v[210:213], v[76:79]
	v_mfma_f32_16x16x32_bf16 v[72:75], v[190:193], v[214:217], v[72:75]
	v_mfma_f32_16x16x32_bf16 v[68:71], v[190:193], v[218:221], v[68:71]
	v_mfma_f32_16x16x32_bf16 v[64:67], v[190:193], v[222:225], v[64:67]
	ds_read_b128 v[176:179], v248
	ds_read_b128 v[182:185], v248 offset:2048
	ds_read_b128 v[186:189], v248 offset:4096
	ds_read_b128 v[190:193], v248 offset:6144
	ds_read_b128 v[226:229], v250 offset:32768
	ds_read_b128 v[230:233], v250 offset:34816
	ds_read_b128 v[234:237], v250 offset:36864
	ds_read_b128 v[238:241], v250 offset:38912
	s_waitcnt lgkmcnt(8)
	v_mfma_f32_16x16x32_bf16 v[60:63], v[194:197], v[210:213], v[60:63]
	v_mfma_f32_16x16x32_bf16 v[56:59], v[194:197], v[214:217], v[56:59]
	v_mfma_f32_16x16x32_bf16 v[52:55], v[194:197], v[218:221], v[52:55]
	v_mfma_f32_16x16x32_bf16 v[48:51], v[194:197], v[222:225], v[48:51]
	v_mfma_f32_16x16x32_bf16 v[44:47], v[198:201], v[210:213], v[44:47]
	v_mfma_f32_16x16x32_bf16 v[40:43], v[198:201], v[214:217], v[40:43]
	v_mfma_f32_16x16x32_bf16 v[36:39], v[198:201], v[218:221], v[36:39]
	v_mfma_f32_16x16x32_bf16 v[32:35], v[198:201], v[222:225], v[32:35]
	v_mfma_f32_16x16x32_bf16 v[28:31], v[202:205], v[210:213], v[28:31]
	v_mfma_f32_16x16x32_bf16 v[24:27], v[202:205], v[214:217], v[24:27]
	v_mfma_f32_16x16x32_bf16 v[20:23], v[202:205], v[218:221], v[20:23]
	v_mfma_f32_16x16x32_bf16 v[16:19], v[202:205], v[222:225], v[16:19]
	v_mfma_f32_16x16x32_bf16 v[8:11], v[206:209], v[210:213], v[8:11]
	v_mfma_f32_16x16x32_bf16 v[0:3], v[206:209], v[214:217], v[0:3]
	v_mfma_f32_16x16x32_bf16 v[12:15], v[206:209], v[218:221], v[12:15]
	v_mfma_f32_16x16x32_bf16 v[4:7], v[206:209], v[222:225], v[4:7]
	ds_read_b128 v[194:197], v248 offset:8192
	ds_read_b128 v[198:201], v248 offset:10240
	ds_read_b128 v[202:205], v248 offset:12288
	ds_read_b128 v[206:209], v248 offset:14336
	s_waitcnt lgkmcnt(4)
	v_mfma_f32_16x16x32_bf16 v[124:127], v[176:179], v[226:229], v[124:127]
	v_mfma_f32_16x16x32_bf16 v[120:123], v[176:179], v[230:233], v[120:123]
	v_mfma_f32_16x16x32_bf16 v[116:119], v[176:179], v[234:237], v[116:119]
	v_mfma_f32_16x16x32_bf16 v[112:115], v[176:179], v[238:241], v[112:115]
	v_mfma_f32_16x16x32_bf16 v[108:111], v[182:185], v[226:229], v[108:111]
	v_mfma_f32_16x16x32_bf16 v[104:107], v[182:185], v[230:233], v[104:107]
	v_mfma_f32_16x16x32_bf16 v[100:103], v[182:185], v[234:237], v[100:103]
	v_mfma_f32_16x16x32_bf16 v[96:99], v[182:185], v[238:241], v[96:99]
	v_mfma_f32_16x16x32_bf16 v[92:95], v[186:189], v[226:229], v[92:95]
	v_mfma_f32_16x16x32_bf16 v[88:91], v[186:189], v[230:233], v[88:91]
	v_mfma_f32_16x16x32_bf16 v[84:87], v[186:189], v[234:237], v[84:87]
	v_mfma_f32_16x16x32_bf16 v[80:83], v[186:189], v[238:241], v[80:83]
	v_mfma_f32_16x16x32_bf16 v[76:79], v[190:193], v[226:229], v[76:79]
	v_mfma_f32_16x16x32_bf16 v[72:75], v[190:193], v[230:233], v[72:75]
	v_mfma_f32_16x16x32_bf16 v[68:71], v[190:193], v[234:237], v[68:71]
	v_mfma_f32_16x16x32_bf16 v[64:67], v[190:193], v[238:241], v[64:67]
	s_add_u32 s68, s68, 0x80
	s_addc_u32 s69, s69, 0
	s_add_i32 s86, s86, 1
	s_branch .Lg5_top

.Lg6_top:
	s_xor_b32 s69, s69, 0x10000
	s_mov_b32 m0, s69
	s_add_u32 s66, s64, s44
	s_addc_u32 s67, s65, s45
	s_waitcnt lgkmcnt(0)
	s_waitcnt vmcnt(0)
	s_barrier
	v_xor_b32_e32 v180, 0x10000, v180
	v_xor_b32_e32 v249, 0x10000, v249
	v_xor_b32_e32 v248, 0x10000, v248
	v_xor_b32_e32 v250, 0x10000, v250
	global_load_lds_dwordx4 v246, s[66:67]
	ds_read_b128 v[182:185], v180
	ds_read_b128 v[186:189], v180 offset:2048
	ds_read_b128 v[190:193], v180 offset:4096
	ds_read_b128 v[194:197], v180 offset:6144
	ds_read_b128 v[214:217], v249 offset:32768
	ds_read_b128 v[218:221], v249 offset:34816
	ds_read_b128 v[222:225], v249 offset:36864
	ds_read_b128 v[226:229], v249 offset:38912
	v_mfma_f32_16x16x32_bf16 v[60:63], v[198:201], v[230:233], v[60:63]
	v_mfma_f32_16x16x32_bf16 v[56:59], v[198:201], v[234:237], v[56:59]
	s_add_u32 m0, s69, 0x2000
	s_add_u32 s66, s64, s46
	s_addc_u32 s67, s65, s47
	global_load_lds_dwordx4 v246, s[66:67]
	v_mfma_f32_16x16x32_bf16 v[52:55], v[198:201], v[238:241], v[52:55]
	v_mfma_f32_16x16x32_bf16 v[48:51], v[198:201], v[242:245], v[48:51]
	s_add_u32 m0, s69, 0x4000
	s_add_u32 s66, s64, s48
	s_addc_u32 s67, s65, s49
	global_load_lds_dwordx4 v246, s[66:67]
	v_mfma_f32_16x16x32_bf16 v[44:47], v[202:205], v[230:233], v[44:47]
	v_mfma_f32_16x16x32_bf16 v[40:43], v[202:205], v[234:237], v[40:43]
	s_add_u32 m0, s69, 0x6000
	s_add_u32 s66, s64, s50
	s_addc_u32 s67, s65, s51
	global_load_lds_dwordx4 v246, s[66:67]
	v_mfma_f32_16x16x32_bf16 v[36:39], v[202:205], v[238:241], v[36:39]
	v_mfma_f32_16x16x32_bf16 v[32:35], v[202:205], v[242:245], v[32:35]
	s_add_u32 m0, s69, 0x8000
	s_add_u32 s66, s64, s52
	s_addc_u32 s67, s65, s53
	global_load_lds_dwordx4 v247, s[66:67]
	v_mfma_f32_16x16x32_bf16 v[28:31], v[206:209], v[230:233], v[28:31]
	v_mfma_f32_16x16x32_bf16 v[24:27], v[206:209], v[234:237], v[24:27]
	s_add_u32 m0, s69, 0xa000
	s_add_u32 s66, s64, s54
	s_addc_u32 s67, s65, s55
	global_load_lds_dwordx4 v247, s[66:67]
	v_mfma_f32_16x16x32_bf16 v[20:23], v[206:209], v[238:241], v[20:23]
	v_mfma_f32_16x16x32_bf16 v[16:19], v[206:209], v[242:245], v[16:19]
	s_add_u32 m0, s69, 0xc000
	s_add_u32 s66, s64, s60
	s_addc_u32 s67, s65, s61
	global_load_lds_dwordx4 v247, s[66:67]
	v_mfma_f32_16x16x32_bf16 v[12:15], v[210:213], v[230:233], v[12:15]
	v_mfma_f32_16x16x32_bf16 v[0:3], v[210:213], v[234:237], v[0:3]
	s_add_u32 m0, s69, 0xe000
	s_add_u32 s66, s64, s62
	s_addc_u32 s67, s65, s63
	global_load_lds_dwordx4 v247, s[66:67]
	v_mfma_f32_16x16x32_bf16 v[8:11], v[210:213], v[238:241], v[8:11]
	v_mfma_f32_16x16x32_bf16 v[4:7], v[210:213], v[242:245], v[4:7]

.Lg7_top:
	s_xor_b32 s61, s61, 0x10000
	s_mov_b32 m0, s61
	s_add_u32 s50, s48, s14
	s_addc_u32 s51, s49, s15
	s_waitcnt lgkmcnt(0)
	s_waitcnt vmcnt(0)
	s_barrier
	global_load_lds_dwordx4 v178, s[50:51]
	ds_read_b128 v[142:145], v141
	ds_read_b128 v[146:149], v141 offset:2048
	ds_read_b128 v[150:153], v141 offset:4096
	ds_read_b128 v[154:157], v141 offset:6144
	ds_read_b128 v[174:177], v210 offset:32768
	ds_read_b128 v[182:185], v210 offset:34816
	ds_read_b128 v[186:189], v210 offset:36864
	ds_read_b128 v[190:193], v210 offset:38912
	v_mfma_f32_16x16x32_bf16 v[60:63], v[158:161], v[194:197], v[60:63]
	v_mfma_f32_16x16x32_bf16 v[56:59], v[158:161], v[198:201], v[56:59]
	s_add_u32 m0, s61, 0x2000
	s_add_u32 s50, s48, s16
	s_addc_u32 s51, s49, s17
	global_load_lds_dwordx4 v178, s[50:51]
	v_mfma_f32_16x16x32_bf16 v[52:55], v[158:161], v[202:205], v[52:55]
	v_mfma_f32_16x16x32_bf16 v[48:51], v[158:161], v[206:209], v[48:51]
	s_add_u32 m0, s61, 0x4000
	s_add_u32 s50, s48, s18
	s_addc_u32 s51, s49, s19
	global_load_lds_dwordx4 v178, s[50:51]
	v_mfma_f32_16x16x32_bf16 v[44:47], v[162:165], v[194:197], v[44:47]
	v_mfma_f32_16x16x32_bf16 v[32:35], v[162:165], v[198:201], v[32:35]
	s_add_u32 m0, s61, 0x6000
	s_add_u32 s50, s48, s22
	s_addc_u32 s51, s49, s23
	global_load_lds_dwordx4 v178, s[50:51]
	v_mfma_f32_16x16x32_bf16 v[28:31], v[162:165], v[202:205], v[28:31]
	v_mfma_f32_16x16x32_bf16 v[24:27], v[162:165], v[206:209], v[24:27]
	s_add_u32 m0, s61, 0x8000
	s_add_u32 s50, s48, s36
	s_addc_u32 s51, s49, s37
	global_load_lds_dwordx4 v179, s[50:51]
	v_mfma_f32_16x16x32_bf16 v[20:23], v[166:169], v[194:197], v[20:23]
	v_mfma_f32_16x16x32_bf16 v[16:19], v[166:169], v[198:201], v[16:19]
	s_add_u32 m0, s61, 0xa000
	s_add_u32 s50, s48, s40
	s_addc_u32 s51, s49, s41
	global_load_lds_dwordx4 v179, s[50:51]
	v_mfma_f32_16x16x32_bf16 v[12:15], v[166:169], v[202:205], v[12:15]
	v_mfma_f32_16x16x32_bf16 v[8:11], v[166:169], v[206:209], v[8:11]
	s_add_u32 m0, s61, 0xc000
	s_add_u32 s50, s48, s42
	s_addc_u32 s51, s49, s43
	global_load_lds_dwordx4 v179, s[50:51]
	v_mfma_f32_16x16x32_bf16 v[4:7], v[170:173], v[194:197], v[4:7]
	v_mfma_f32_16x16x32_bf16 v[0:3], v[170:173], v[198:201], v[0:3]
	s_add_u32 m0, s61, 0xe000
	s_add_u32 s50, s48, s44
	s_addc_u32 s51, s49, s45
	global_load_lds_dwordx4 v179, s[50:51]
	v_mfma_f32_16x16x32_bf16 v[40:43], v[170:173], v[202:205], v[40:43]
	v_mfma_f32_16x16x32_bf16 v[36:39], v[170:173], v[206:209], v[36:39]
.Lg7_entry:
	ds_read_b128 v[158:161], v141 offset:8192
	ds_read_b128 v[162:165], v141 offset:10240
	ds_read_b128 v[166:169], v141 offset:12288
	ds_read_b128 v[170:173], v141 offset:14336
	s_waitcnt lgkmcnt(4)
	v_mfma_f32_16x16x32_bf16 v[124:127], v[142:145], v[174:177], v[124:127]
	v_mfma_f32_16x16x32_bf16 v[120:123], v[142:145], v[182:185], v[120:123]
	v_mfma_f32_16x16x32_bf16 v[116:119], v[142:145], v[186:189], v[116:119]
	v_mfma_f32_16x16x32_bf16 v[112:115], v[142:145], v[190:193], v[112:115]
	v_mfma_f32_16x16x32_bf16 v[108:111], v[146:149], v[174:177], v[108:111]
	v_mfma_f32_16x16x32_bf16 v[104:107], v[146:149], v[182:185], v[104:107]
	v_mfma_f32_16x16x32_bf16 v[100:103], v[146:149], v[186:189], v[100:103]
	v_mfma_f32_16x16x32_bf16 v[96:99], v[146:149], v[190:193], v[96:99]
	v_mfma_f32_16x16x32_bf16 v[92:95], v[150:153], v[174:177], v[92:95]
	v_mfma_f32_16x16x32_bf16 v[88:91], v[150:153], v[182:185], v[88:91]
	v_mfma_f32_16x16x32_bf16 v[84:87], v[150:153], v[186:189], v[84:87]
	v_mfma_f32_16x16x32_bf16 v[80:83], v[150:153], v[190:193], v[80:83]
	v_mfma_f32_16x16x32_bf16 v[76:79], v[154:157], v[174:177], v[76:79]
	v_mfma_f32_16x16x32_bf16 v[72:75], v[154:157], v[182:185], v[72:75]
	v_mfma_f32_16x16x32_bf16 v[68:71], v[154:157], v[186:189], v[68:71]
	v_mfma_f32_16x16x32_bf16 v[64:67], v[154:157], v[190:193], v[64:67]
	ds_read_b128 v[142:145], v180
	ds_read_b128 v[146:149], v180 offset:2048
	ds_read_b128 v[150:153], v180 offset:4096
	ds_read_b128 v[154:157], v180 offset:6144
	ds_read_b128 v[194:197], v211 offset:32768
	ds_read_b128 v[198:201], v211 offset:34816
	ds_read_b128 v[202:205], v211 offset:36864
	ds_read_b128 v[206:209], v211 offset:38912
	s_waitcnt lgkmcnt(8)
	v_mfma_f32_16x16x32_bf16 v[60:63], v[158:161], v[174:177], v[60:63]
	v_mfma_f32_16x16x32_bf16 v[56:59], v[158:161], v[182:185], v[56:59]
	v_mfma_f32_16x16x32_bf16 v[52:55], v[158:161], v[186:189], v[52:55]
	v_mfma_f32_16x16x32_bf16 v[48:51], v[158:161], v[190:193], v[48:51]
	v_mfma_f32_16x16x32_bf16 v[44:47], v[162:165], v[174:177], v[44:47]
	v_mfma_f32_16x16x32_bf16 v[32:35], v[162:165], v[182:185], v[32:35]
	v_mfma_f32_16x16x32_bf16 v[28:31], v[162:165], v[186:189], v[28:31]
	v_mfma_f32_16x16x32_bf16 v[24:27], v[162:165], v[190:193], v[24:27]
	v_mfma_f32_16x16x32_bf16 v[20:23], v[166:169], v[174:177], v[20:23]
	v_mfma_f32_16x16x32_bf16 v[16:19], v[166:169], v[182:185], v[16:19]
	v_mfma_f32_16x16x32_bf16 v[12:15], v[166:169], v[186:189], v[12:15]
	v_mfma_f32_16x16x32_bf16 v[8:11], v[166:169], v[190:193], v[8:11]
	v_mfma_f32_16x16x32_bf16 v[4:7], v[170:173], v[174:177], v[4:7]
	v_mfma_f32_16x16x32_bf16 v[0:3], v[170:173], v[182:185], v[0:3]
	v_mfma_f32_16x16x32_bf16 v[40:43], v[170:173], v[186:189], v[40:43]
	v_mfma_f32_16x16x32_bf16 v[36:39], v[170:173], v[190:193], v[36:39]
	ds_read_b128 v[158:161], v180 offset:8192
	ds_read_b128 v[162:165], v180 offset:10240
	ds_read_b128 v[166:169], v180 offset:12288
	ds_read_b128 v[170:173], v180 offset:14336
	s_waitcnt lgkmcnt(4)
	v_mfma_f32_16x16x32_bf16 v[124:127], v[142:145], v[194:197], v[124:127]
	v_mfma_f32_16x16x32_bf16 v[120:123], v[142:145], v[198:201], v[120:123]
	v_mfma_f32_16x16x32_bf16 v[116:119], v[142:145], v[202:205], v[116:119]
	v_mfma_f32_16x16x32_bf16 v[112:115], v[142:145], v[206:209], v[112:115]
	v_mfma_f32_16x16x32_bf16 v[108:111], v[146:149], v[194:197], v[108:111]
	v_mfma_f32_16x16x32_bf16 v[104:107], v[146:149], v[198:201], v[104:107]
	v_mfma_f32_16x16x32_bf16 v[100:103], v[146:149], v[202:205], v[100:103]
	v_mfma_f32_16x16x32_bf16 v[96:99], v[146:149], v[206:209], v[96:99]
	v_mfma_f32_16x16x32_bf16 v[92:95], v[150:153], v[194:197], v[92:95]
	v_mfma_f32_16x16x32_bf16 v[88:91], v[150:153], v[198:201], v[88:91]
	v_mfma_f32_16x16x32_bf16 v[84:87], v[150:153], v[202:205], v[84:87]
	v_mfma_f32_16x16x32_bf16 v[80:83], v[150:153], v[206:209], v[80:83]
	v_mfma_f32_16x16x32_bf16 v[76:79], v[154:157], v[194:197], v[76:79]
	v_mfma_f32_16x16x32_bf16 v[72:75], v[154:157], v[198:201], v[72:75]
	v_mfma_f32_16x16x32_bf16 v[68:71], v[154:157], v[202:205], v[68:71]
	v_mfma_f32_16x16x32_bf16 v[64:67], v[154:157], v[206:209], v[64:67]
	s_add_u32 s48, s48, 0x80
	s_addc_u32 s49, s49, 0
	s_add_i32 s47, s47, 1
	s_cmp_lt_u32 s47, 31
	s_cbranch_scc0 .Lg7_last
	s_xor_b32 s61, s61, 0x10000
	s_mov_b32 m0, s61
	s_add_u32 s50, s48, s14
	s_addc_u32 s51, s49, s15
	s_waitcnt lgkmcnt(0)
	s_waitcnt vmcnt(0)
	s_barrier
	global_load_lds_dwordx4 v178, s[50:51]
	ds_read_b128 v[142:145], v212
	ds_read_b128 v[146:149], v212 offset:2048
	ds_read_b128 v[150:153], v212 offset:4096
	ds_read_b128 v[154:157], v212 offset:6144
	ds_read_b128 v[174:177], v214 offset:32768
	ds_read_b128 v[182:185], v214 offset:34816
	ds_read_b128 v[186:189], v214 offset:36864
	ds_read_b128 v[190:193], v214 offset:38912
	v_mfma_f32_16x16x32_bf16 v[60:63], v[158:161], v[194:197], v[60:63]
	v_mfma_f32_16x16x32_bf16 v[56:59], v[158:161], v[198:201], v[56:59]
	s_add_u32 m0, s61, 0x2000
	s_add_u32 s50, s48, s16
	s_addc_u32 s51, s49, s17
	global_load_lds_dwordx4 v178, s[50:51]
	v_mfma_f32_16x16x32_bf16 v[52:55], v[158:161], v[202:205], v[52:55]
	v_mfma_f32_16x16x32_bf16 v[48:51], v[158:161], v[206:209], v[48:51]
	s_add_u32 m0, s61, 0x4000
	s_add_u32 s50, s48, s18
	s_addc_u32 s51, s49, s19
	global_load_lds_dwordx4 v178, s[50:51]
	v_mfma_f32_16x16x32_bf16 v[44:47], v[162:165], v[194:197], v[44:47]
	v_mfma_f32_16x16x32_bf16 v[32:35], v[162:165], v[198:201], v[32:35]
	s_add_u32 m0, s61, 0x6000
	s_add_u32 s50, s48, s22
	s_addc_u32 s51, s49, s23
	global_load_lds_dwordx4 v178, s[50:51]
	v_mfma_f32_16x16x32_bf16 v[28:31], v[162:165], v[202:205], v[28:31]
	v_mfma_f32_16x16x32_bf16 v[24:27], v[162:165], v[206:209], v[24:27]
	s_add_u32 m0, s61, 0x8000
	s_add_u32 s50, s48, s36
	s_addc_u32 s51, s49, s37
	global_load_lds_dwordx4 v179, s[50:51]
	v_mfma_f32_16x16x32_bf16 v[20:23], v[166:169], v[194:197], v[20:23]
	v_mfma_f32_16x16x32_bf16 v[16:19], v[166:169], v[198:201], v[16:19]
	s_add_u32 m0, s61, 0xa000
	s_add_u32 s50, s48, s40
	s_addc_u32 s51, s49, s41
	global_load_lds_dwordx4 v179, s[50:51]
	v_mfma_f32_16x16x32_bf16 v[12:15], v[166:169], v[202:205], v[12:15]
	v_mfma_f32_16x16x32_bf16 v[8:11], v[166:169], v[206:209], v[8:11]
	s_add_u32 m0, s61, 0xc000
	s_add_u32 s50, s48, s42
	s_addc_u32 s51, s49, s43
	global_load_lds_dwordx4 v179, s[50:51]
	v_mfma_f32_16x16x32_bf16 v[4:7], v[170:173], v[194:197], v[4:7]
	v_mfma_f32_16x16x32_bf16 v[0:3], v[170:173], v[198:201], v[0:3]
	s_add_u32 m0, s61, 0xe000
	s_add_u32 s50, s48, s44
	s_addc_u32 s51, s49, s45
	global_load_lds_dwordx4 v179, s[50:51]
	v_mfma_f32_16x16x32_bf16 v[40:43], v[170:173], v[202:205], v[40:43]
	v_mfma_f32_16x16x32_bf16 v[36:39], v[170:173], v[206:209], v[36:39]
	ds_read_b128 v[158:161], v212 offset:8192
	ds_read_b128 v[162:165], v212 offset:10240
	ds_read_b128 v[166:169], v212 offset:12288
	ds_read_b128 v[170:173], v212 offset:14336
	s_waitcnt lgkmcnt(4)
	v_mfma_f32_16x16x32_bf16 v[124:127], v[142:145], v[174:177], v[124:127]
	v_mfma_f32_16x16x32_bf16 v[120:123], v[142:145], v[182:185], v[120:123]
	v_mfma_f32_16x16x32_bf16 v[116:119], v[142:145], v[186:189], v[116:119]
	v_mfma_f32_16x16x32_bf16 v[112:115], v[142:145], v[190:193], v[112:115]
	v_mfma_f32_16x16x32_bf16 v[108:111], v[146:149], v[174:177], v[108:111]
	v_mfma_f32_16x16x32_bf16 v[104:107], v[146:149], v[182:185], v[104:107]
	v_mfma_f32_16x16x32_bf16 v[100:103], v[146:149], v[186:189], v[100:103]
	v_mfma_f32_16x16x32_bf16 v[96:99], v[146:149], v[190:193], v[96:99]
	v_mfma_f32_16x16x32_bf16 v[92:95], v[150:153], v[174:177], v[92:95]
	v_mfma_f32_16x16x32_bf16 v[88:91], v[150:153], v[182:185], v[88:91]
	v_mfma_f32_16x16x32_bf16 v[84:87], v[150:153], v[186:189], v[84:87]
	v_mfma_f32_16x16x32_bf16 v[80:83], v[150:153], v[190:193], v[80:83]
	v_mfma_f32_16x16x32_bf16 v[76:79], v[154:157], v[174:177], v[76:79]
	v_mfma_f32_16x16x32_bf16 v[72:75], v[154:157], v[182:185], v[72:75]
	v_mfma_f32_16x16x32_bf16 v[68:71], v[154:157], v[186:189], v[68:71]
	v_mfma_f32_16x16x32_bf16 v[64:67], v[154:157], v[190:193], v[64:67]
	ds_read_b128 v[142:145], v213
	ds_read_b128 v[146:149], v213 offset:2048
	ds_read_b128 v[150:153], v213 offset:4096
	ds_read_b128 v[154:157], v213 offset:6144
	ds_read_b128 v[194:197], v215 offset:32768
	ds_read_b128 v[198:201], v215 offset:34816
	ds_read_b128 v[202:205], v215 offset:36864
	ds_read_b128 v[206:209], v215 offset:38912
	s_waitcnt lgkmcnt(8)
	v_mfma_f32_16x16x32_bf16 v[60:63], v[158:161], v[174:177], v[60:63]
	v_mfma_f32_16x16x32_bf16 v[56:59], v[158:161], v[182:185], v[56:59]
	v_mfma_f32_16x16x32_bf16 v[52:55], v[158:161], v[186:189], v[52:55]
	v_mfma_f32_16x16x32_bf16 v[48:51], v[158:161], v[190:193], v[48:51]
	v_mfma_f32_16x16x32_bf16 v[44:47], v[162:165], v[174:177], v[44:47]
	v_mfma_f32_16x16x32_bf16 v[32:35], v[162:165], v[182:185], v[32:35]
	v_mfma_f32_16x16x32_bf16 v[28:31], v[162:165], v[186:189], v[28:31]
	v_mfma_f32_16x16x32_bf16 v[24:27], v[162:165], v[190:193], v[24:27]
	v_mfma_f32_16x16x32_bf16 v[20:23], v[166:169], v[174:177], v[20:23]
	v_mfma_f32_16x16x32_bf16 v[16:19], v[166:169], v[182:185], v[16:19]
	v_mfma_f32_16x16x32_bf16 v[12:15], v[166:169], v[186:189], v[12:15]
	v_mfma_f32_16x16x32_bf16 v[8:11], v[166:169], v[190:193], v[8:11]
	v_mfma_f32_16x16x32_bf16 v[4:7], v[170:173], v[174:177], v[4:7]
	v_mfma_f32_16x16x32_bf16 v[0:3], v[170:173], v[182:185], v[0:3]
	v_mfma_f32_16x16x32_bf16 v[40:43], v[170:173], v[186:189], v[40:43]
	v_mfma_f32_16x16x32_bf16 v[36:39], v[170:173], v[190:193], v[36:39]
	ds_read_b128 v[158:161], v213 offset:8192
	ds_read_b128 v[162:165], v213 offset:10240
	ds_read_b128 v[166:169], v213 offset:12288
	ds_read_b128 v[170:173], v213 offset:14336
	s_waitcnt lgkmcnt(4)
	v_mfma_f32_16x16x32_bf16 v[124:127], v[142:145], v[194:197], v[124:127]
	v_mfma_f32_16x16x32_bf16 v[120:123], v[142:145], v[198:201], v[120:123]
	v_mfma_f32_16x16x32_bf16 v[116:119], v[142:145], v[202:205], v[116:119]
	v_mfma_f32_16x16x32_bf16 v[112:115], v[142:145], v[206:209], v[112:115]
	v_mfma_f32_16x16x32_bf16 v[108:111], v[146:149], v[194:197], v[108:111]
	v_mfma_f32_16x16x32_bf16 v[104:107], v[146:149], v[198:201], v[104:107]
	v_mfma_f32_16x16x32_bf16 v[100:103], v[146:149], v[202:205], v[100:103]
	v_mfma_f32_16x16x32_bf16 v[96:99], v[146:149], v[206:209], v[96:99]
	v_mfma_f32_16x16x32_bf16 v[92:95], v[150:153], v[194:197], v[92:95]
	v_mfma_f32_16x16x32_bf16 v[88:91], v[150:153], v[198:201], v[88:91]
	v_mfma_f32_16x16x32_bf16 v[84:87], v[150:153], v[202:205], v[84:87]
	v_mfma_f32_16x16x32_bf16 v[80:83], v[150:153], v[206:209], v[80:83]
	v_mfma_f32_16x16x32_bf16 v[76:79], v[154:157], v[194:197], v[76:79]
	v_mfma_f32_16x16x32_bf16 v[72:75], v[154:157], v[198:201], v[72:75]
	v_mfma_f32_16x16x32_bf16 v[68:71], v[154:157], v[202:205], v[68:71]
	v_mfma_f32_16x16x32_bf16 v[64:67], v[154:157], v[206:209], v[64:67]
	s_add_u32 s48, s48, 0x80
	s_addc_u32 s49, s49, 0
	s_add_i32 s47, s47, 1
	s_branch .Lg7_top

.Lg8_top:
	s_xor_b32 s59, s59, 0x10000
	s_mov_b32 m0, s59
	s_add_u32 s62, s60, s22
	s_addc_u32 s63, s61, s23
	s_waitcnt lgkmcnt(0)
	s_waitcnt vmcnt(0)
	s_barrier
	global_load_lds_dwordx4 v178, s[62:63]
	ds_read_b128 v[154:157], v180
	ds_read_b128 v[158:161], v180 offset:2048
	ds_read_b128 v[162:165], v180 offset:4096
	ds_read_b128 v[166:169], v180 offset:6144
	ds_read_b128 v[190:193], v223 offset:32768
	ds_read_b128 v[194:197], v223 offset:34816
	ds_read_b128 v[198:201], v223 offset:36864
	ds_read_b128 v[202:205], v223 offset:38912
	v_mfma_f32_16x16x32_bf16 v[60:63], v[170:173], v[206:209], v[60:63]
	v_mfma_f32_16x16x32_bf16 v[56:59], v[170:173], v[210:213], v[56:59]
	s_add_u32 m0, s59, 0x2000
	s_add_u32 s62, s60, s36
	s_addc_u32 s63, s61, s37
	global_load_lds_dwordx4 v178, s[62:63]
	v_mfma_f32_16x16x32_bf16 v[52:55], v[170:173], v[214:217], v[52:55]
	v_mfma_f32_16x16x32_bf16 v[44:47], v[170:173], v[218:221], v[44:47]
	s_add_u32 m0, s59, 0x4000
	s_add_u32 s62, s60, s38
	s_addc_u32 s63, s61, s39
	global_load_lds_dwordx4 v178, s[62:63]
	v_mfma_f32_16x16x32_bf16 v[36:39], v[174:177], v[206:209], v[36:39]
	v_mfma_f32_16x16x32_bf16 v[32:35], v[174:177], v[210:213], v[32:35]
	s_add_u32 m0, s59, 0x6000
	s_add_u32 s62, s60, s40
	s_addc_u32 s63, s61, s41
	global_load_lds_dwordx4 v178, s[62:63]
	v_mfma_f32_16x16x32_bf16 v[28:31], v[174:177], v[214:217], v[28:31]
	v_mfma_f32_16x16x32_bf16 v[24:27], v[174:177], v[218:221], v[24:27]
	s_add_u32 m0, s59, 0x8000
	s_add_u32 s62, s60, s42
	s_addc_u32 s63, s61, s43
	global_load_lds_dwordx4 v179, s[62:63]
	v_mfma_f32_16x16x32_bf16 v[20:23], v[182:185], v[206:209], v[20:23]
	v_mfma_f32_16x16x32_bf16 v[16:19], v[182:185], v[210:213], v[16:19]
	s_add_u32 m0, s59, 0xa000
	s_add_u32 s62, s60, s44
	s_addc_u32 s63, s61, s45
	global_load_lds_dwordx4 v179, s[62:63]
	v_mfma_f32_16x16x32_bf16 v[12:15], v[182:185], v[214:217], v[12:15]
	v_mfma_f32_16x16x32_bf16 v[8:11], v[182:185], v[218:221], v[8:11]
	s_add_u32 m0, s59, 0xc000
	s_add_u32 s62, s60, s46
	s_addc_u32 s63, s61, s47
	global_load_lds_dwordx4 v179, s[62:63]
	v_mfma_f32_16x16x32_bf16 v[4:7], v[186:189], v[206:209], v[4:7]
	v_mfma_f32_16x16x32_bf16 v[0:3], v[186:189], v[210:213], v[0:3]
	s_add_u32 m0, s59, 0xe000
	s_add_u32 s62, s60, s48
	s_addc_u32 s63, s61, s49
	global_load_lds_dwordx4 v179, s[62:63]
	v_mfma_f32_16x16x32_bf16 v[48:51], v[186:189], v[214:217], v[48:51]
	v_mfma_f32_16x16x32_bf16 v[40:43], v[186:189], v[218:221], v[40:43]
.Lg8_entry:
	ds_read_b128 v[170:173], v180 offset:8192
	ds_read_b128 v[174:177], v180 offset:10240
	ds_read_b128 v[182:185], v180 offset:12288
	ds_read_b128 v[186:189], v180 offset:14336
	s_waitcnt lgkmcnt(4)
	v_mfma_f32_16x16x32_bf16 v[124:127], v[154:157], v[190:193], v[124:127]
	v_mfma_f32_16x16x32_bf16 v[120:123], v[154:157], v[194:197], v[120:123]
	v_mfma_f32_16x16x32_bf16 v[116:119], v[154:157], v[198:201], v[116:119]
	v_mfma_f32_16x16x32_bf16 v[112:115], v[154:157], v[202:205], v[112:115]
	v_mfma_f32_16x16x32_bf16 v[108:111], v[158:161], v[190:193], v[108:111]
	v_mfma_f32_16x16x32_bf16 v[104:107], v[158:161], v[194:197], v[104:107]
	v_mfma_f32_16x16x32_bf16 v[100:103], v[158:161], v[198:201], v[100:103]
	v_mfma_f32_16x16x32_bf16 v[96:99], v[158:161], v[202:205], v[96:99]
	v_mfma_f32_16x16x32_bf16 v[92:95], v[162:165], v[190:193], v[92:95]
	v_mfma_f32_16x16x32_bf16 v[88:91], v[162:165], v[194:197], v[88:91]
	v_mfma_f32_16x16x32_bf16 v[84:87], v[162:165], v[198:201], v[84:87]
	v_mfma_f32_16x16x32_bf16 v[80:83], v[162:165], v[202:205], v[80:83]
	v_mfma_f32_16x16x32_bf16 v[76:79], v[166:169], v[190:193], v[76:79]
	v_mfma_f32_16x16x32_bf16 v[72:75], v[166:169], v[194:197], v[72:75]
	v_mfma_f32_16x16x32_bf16 v[68:71], v[166:169], v[198:201], v[68:71]
	v_mfma_f32_16x16x32_bf16 v[64:67], v[166:169], v[202:205], v[64:67]
	ds_read_b128 v[154:157], v222
	ds_read_b128 v[158:161], v222 offset:2048
	ds_read_b128 v[162:165], v222 offset:4096
	ds_read_b128 v[166:169], v222 offset:6144
	ds_read_b128 v[206:209], v224 offset:32768
	ds_read_b128 v[210:213], v224 offset:34816
	ds_read_b128 v[214:217], v224 offset:36864
	ds_read_b128 v[218:221], v224 offset:38912
	s_waitcnt lgkmcnt(8)
	v_mfma_f32_16x16x32_bf16 v[60:63], v[170:173], v[190:193], v[60:63]
	v_mfma_f32_16x16x32_bf16 v[56:59], v[170:173], v[194:197], v[56:59]
	v_mfma_f32_16x16x32_bf16 v[52:55], v[170:173], v[198:201], v[52:55]
	v_mfma_f32_16x16x32_bf16 v[44:47], v[170:173], v[202:205], v[44:47]
	v_mfma_f32_16x16x32_bf16 v[36:39], v[174:177], v[190:193], v[36:39]
	v_mfma_f32_16x16x32_bf16 v[32:35], v[174:177], v[194:197], v[32:35]
	v_mfma_f32_16x16x32_bf16 v[28:31], v[174:177], v[198:201], v[28:31]
	v_mfma_f32_16x16x32_bf16 v[24:27], v[174:177], v[202:205], v[24:27]
	v_mfma_f32_16x16x32_bf16 v[20:23], v[182:185], v[190:193], v[20:23]
	v_mfma_f32_16x16x32_bf16 v[16:19], v[182:185], v[194:197], v[16:19]
	v_mfma_f32_16x16x32_bf16 v[12:15], v[182:185], v[198:201], v[12:15]
	v_mfma_f32_16x16x32_bf16 v[8:11], v[182:185], v[202:205], v[8:11]
	v_mfma_f32_16x16x32_bf16 v[4:7], v[186:189], v[190:193], v[4:7]
	v_mfma_f32_16x16x32_bf16 v[0:3], v[186:189], v[194:197], v[0:3]
	v_mfma_f32_16x16x32_bf16 v[48:51], v[186:189], v[198:201], v[48:51]
	v_mfma_f32_16x16x32_bf16 v[40:43], v[186:189], v[202:205], v[40:43]
	ds_read_b128 v[170:173], v222 offset:8192
	ds_read_b128 v[174:177], v222 offset:10240
	ds_read_b128 v[182:185], v222 offset:12288
	ds_read_b128 v[186:189], v222 offset:14336
	s_waitcnt lgkmcnt(4)
	v_mfma_f32_16x16x32_bf16 v[124:127], v[154:157], v[206:209], v[124:127]
	v_mfma_f32_16x16x32_bf16 v[120:123], v[154:157], v[210:213], v[120:123]
	v_mfma_f32_16x16x32_bf16 v[116:119], v[154:157], v[214:217], v[116:119]
	v_mfma_f32_16x16x32_bf16 v[112:115], v[154:157], v[218:221], v[112:115]
	v_mfma_f32_16x16x32_bf16 v[108:111], v[158:161], v[206:209], v[108:111]
	v_mfma_f32_16x16x32_bf16 v[104:107], v[158:161], v[210:213], v[104:107]
	v_mfma_f32_16x16x32_bf16 v[100:103], v[158:161], v[214:217], v[100:103]
	v_mfma_f32_16x16x32_bf16 v[96:99], v[158:161], v[218:221], v[96:99]
	v_mfma_f32_16x16x32_bf16 v[92:95], v[162:165], v[206:209], v[92:95]
	v_mfma_f32_16x16x32_bf16 v[88:91], v[162:165], v[210:213], v[88:91]
	v_mfma_f32_16x16x32_bf16 v[84:87], v[162:165], v[214:217], v[84:87]
	v_mfma_f32_16x16x32_bf16 v[80:83], v[162:165], v[218:221], v[80:83]
	v_mfma_f32_16x16x32_bf16 v[76:79], v[166:169], v[206:209], v[76:79]
	v_mfma_f32_16x16x32_bf16 v[72:75], v[166:169], v[210:213], v[72:75]
	v_mfma_f32_16x16x32_bf16 v[68:71], v[166:169], v[214:217], v[68:71]
	v_mfma_f32_16x16x32_bf16 v[64:67], v[166:169], v[218:221], v[64:67]
	s_add_u32 s60, s60, 0x80
	s_addc_u32 s61, s61, 0
	s_add_i32 s57, s57, 1
	s_cmp_lt_u32 s57, 15
	s_cbranch_scc0 .Lg8_last
	s_xor_b32 s59, s59, 0x10000
	s_mov_b32 m0, s59
	s_add_u32 s62, s60, s22
	s_addc_u32 s63, s61, s23
	s_waitcnt lgkmcnt(0)
	s_waitcnt vmcnt(0)
	s_barrier
	global_load_lds_dwordx4 v178, s[62:63]
	ds_read_b128 v[154:157], v225
	ds_read_b128 v[158:161], v225 offset:2048
	ds_read_b128 v[162:165], v225 offset:4096
	ds_read_b128 v[166:169], v225 offset:6144
	ds_read_b128 v[190:193], v227 offset:32768
	ds_read_b128 v[194:197], v227 offset:34816
	ds_read_b128 v[198:201], v227 offset:36864
	ds_read_b128 v[202:205], v227 offset:38912
	v_mfma_f32_16x16x32_bf16 v[60:63], v[170:173], v[206:209], v[60:63]
	v_mfma_f32_16x16x32_bf16 v[56:59], v[170:173], v[210:213], v[56:59]
	s_add_u32 m0, s59, 0x2000
	s_add_u32 s62, s60, s36
	s_addc_u32 s63, s61, s37
	global_load_lds_dwordx4 v178, s[62:63]
	v_mfma_f32_16x16x32_bf16 v[52:55], v[170:173], v[214:217], v[52:55]
	v_mfma_f32_16x16x32_bf16 v[44:47], v[170:173], v[218:221], v[44:47]
	s_add_u32 m0, s59, 0x4000
	s_add_u32 s62, s60, s38
	s_addc_u32 s63, s61, s39
	global_load_lds_dwordx4 v178, s[62:63]
	v_mfma_f32_16x16x32_bf16 v[36:39], v[174:177], v[206:209], v[36:39]
	v_mfma_f32_16x16x32_bf16 v[32:35], v[174:177], v[210:213], v[32:35]
	s_add_u32 m0, s59, 0x6000
	s_add_u32 s62, s60, s40
	s_addc_u32 s63, s61, s41
	global_load_lds_dwordx4 v178, s[62:63]
	v_mfma_f32_16x16x32_bf16 v[28:31], v[174:177], v[214:217], v[28:31]
	v_mfma_f32_16x16x32_bf16 v[24:27], v[174:177], v[218:221], v[24:27]
	s_add_u32 m0, s59, 0x8000
	s_add_u32 s62, s60, s42
	s_addc_u32 s63, s61, s43
	global_load_lds_dwordx4 v179, s[62:63]
	v_mfma_f32_16x16x32_bf16 v[20:23], v[182:185], v[206:209], v[20:23]
	v_mfma_f32_16x16x32_bf16 v[16:19], v[182:185], v[210:213], v[16:19]
	s_add_u32 m0, s59, 0xa000
	s_add_u32 s62, s60, s44
	s_addc_u32 s63, s61, s45
	global_load_lds_dwordx4 v179, s[62:63]
	v_mfma_f32_16x16x32_bf16 v[12:15], v[182:185], v[214:217], v[12:15]
	v_mfma_f32_16x16x32_bf16 v[8:11], v[182:185], v[218:221], v[8:11]
	s_add_u32 m0, s59, 0xc000
	s_add_u32 s62, s60, s46
	s_addc_u32 s63, s61, s47
	global_load_lds_dwordx4 v179, s[62:63]
	v_mfma_f32_16x16x32_bf16 v[4:7], v[186:189], v[206:209], v[4:7]
	v_mfma_f32_16x16x32_bf16 v[0:3], v[186:189], v[210:213], v[0:3]
	s_add_u32 m0, s59, 0xe000
	s_add_u32 s62, s60, s48
	s_addc_u32 s63, s61, s49
	global_load_lds_dwordx4 v179, s[62:63]
	v_mfma_f32_16x16x32_bf16 v[48:51], v[186:189], v[214:217], v[48:51]
	v_mfma_f32_16x16x32_bf16 v[40:43], v[186:189], v[218:221], v[40:43]
	ds_read_b128 v[170:173], v225 offset:8192
	ds_read_b128 v[174:177], v225 offset:10240
	ds_read_b128 v[182:185], v225 offset:12288
	ds_read_b128 v[186:189], v225 offset:14336
	s_waitcnt lgkmcnt(4)
	v_mfma_f32_16x16x32_bf16 v[124:127], v[154:157], v[190:193], v[124:127]
	v_mfma_f32_16x16x32_bf16 v[120:123], v[154:157], v[194:197], v[120:123]
	v_mfma_f32_16x16x32_bf16 v[116:119], v[154:157], v[198:201], v[116:119]
	v_mfma_f32_16x16x32_bf16 v[112:115], v[154:157], v[202:205], v[112:115]
	v_mfma_f32_16x16x32_bf16 v[108:111], v[158:161], v[190:193], v[108:111]
	v_mfma_f32_16x16x32_bf16 v[104:107], v[158:161], v[194:197], v[104:107]
	v_mfma_f32_16x16x32_bf16 v[100:103], v[158:161], v[198:201], v[100:103]
	v_mfma_f32_16x16x32_bf16 v[96:99], v[158:161], v[202:205], v[96:99]
	v_mfma_f32_16x16x32_bf16 v[92:95], v[162:165], v[190:193], v[92:95]
	v_mfma_f32_16x16x32_bf16 v[88:91], v[162:165], v[194:197], v[88:91]
	v_mfma_f32_16x16x32_bf16 v[84:87], v[162:165], v[198:201], v[84:87]
	v_mfma_f32_16x16x32_bf16 v[80:83], v[162:165], v[202:205], v[80:83]
	v_mfma_f32_16x16x32_bf16 v[76:79], v[166:169], v[190:193], v[76:79]
	v_mfma_f32_16x16x32_bf16 v[72:75], v[166:169], v[194:197], v[72:75]
	v_mfma_f32_16x16x32_bf16 v[68:71], v[166:169], v[198:201], v[68:71]
	v_mfma_f32_16x16x32_bf16 v[64:67], v[166:169], v[202:205], v[64:67]
	ds_read_b128 v[154:157], v226
	ds_read_b128 v[158:161], v226 offset:2048
	ds_read_b128 v[162:165], v226 offset:4096
	ds_read_b128 v[166:169], v226 offset:6144
	ds_read_b128 v[206:209], v228 offset:32768
	ds_read_b128 v[210:213], v228 offset:34816
	ds_read_b128 v[214:217], v228 offset:36864
	ds_read_b128 v[218:221], v228 offset:38912
	s_waitcnt lgkmcnt(8)
	v_mfma_f32_16x16x32_bf16 v[60:63], v[170:173], v[190:193], v[60:63]
	v_mfma_f32_16x16x32_bf16 v[56:59], v[170:173], v[194:197], v[56:59]
	v_mfma_f32_16x16x32_bf16 v[52:55], v[170:173], v[198:201], v[52:55]
	v_mfma_f32_16x16x32_bf16 v[44:47], v[170:173], v[202:205], v[44:47]
	v_mfma_f32_16x16x32_bf16 v[36:39], v[174:177], v[190:193], v[36:39]
	v_mfma_f32_16x16x32_bf16 v[32:35], v[174:177], v[194:197], v[32:35]
	v_mfma_f32_16x16x32_bf16 v[28:31], v[174:177], v[198:201], v[28:31]
	v_mfma_f32_16x16x32_bf16 v[24:27], v[174:177], v[202:205], v[24:27]
	v_mfma_f32_16x16x32_bf16 v[20:23], v[182:185], v[190:193], v[20:23]
	v_mfma_f32_16x16x32_bf16 v[16:19], v[182:185], v[194:197], v[16:19]
	v_mfma_f32_16x16x32_bf16 v[12:15], v[182:185], v[198:201], v[12:15]
	v_mfma_f32_16x16x32_bf16 v[8:11], v[182:185], v[202:205], v[8:11]
	v_mfma_f32_16x16x32_bf16 v[4:7], v[186:189], v[190:193], v[4:7]
	v_mfma_f32_16x16x32_bf16 v[0:3], v[186:189], v[194:197], v[0:3]
	v_mfma_f32_16x16x32_bf16 v[48:51], v[186:189], v[198:201], v[48:51]
	v_mfma_f32_16x16x32_bf16 v[40:43], v[186:189], v[202:205], v[40:43]
	ds_read_b128 v[170:173], v226 offset:8192
	ds_read_b128 v[174:177], v226 offset:10240
	ds_read_b128 v[182:185], v226 offset:12288
	ds_read_b128 v[186:189], v226 offset:14336
	s_waitcnt lgkmcnt(4)
	v_mfma_f32_16x16x32_bf16 v[124:127], v[154:157], v[206:209], v[124:127]
	v_mfma_f32_16x16x32_bf16 v[120:123], v[154:157], v[210:213], v[120:123]
	v_mfma_f32_16x16x32_bf16 v[116:119], v[154:157], v[214:217], v[116:119]
	v_mfma_f32_16x16x32_bf16 v[112:115], v[154:157], v[218:221], v[112:115]
	v_mfma_f32_16x16x32_bf16 v[108:111], v[158:161], v[206:209], v[108:111]
	v_mfma_f32_16x16x32_bf16 v[104:107], v[158:161], v[210:213], v[104:107]
	v_mfma_f32_16x16x32_bf16 v[100:103], v[158:161], v[214:217], v[100:103]
	v_mfma_f32_16x16x32_bf16 v[96:99], v[158:161], v[218:221], v[96:99]
	v_mfma_f32_16x16x32_bf16 v[92:95], v[162:165], v[206:209], v[92:95]
	v_mfma_f32_16x16x32_bf16 v[88:91], v[162:165], v[210:213], v[88:91]
	v_mfma_f32_16x16x32_bf16 v[84:87], v[162:165], v[214:217], v[84:87]
	v_mfma_f32_16x16x32_bf16 v[80:83], v[162:165], v[218:221], v[80:83]
	v_mfma_f32_16x16x32_bf16 v[76:79], v[166:169], v[206:209], v[76:79]
	v_mfma_f32_16x16x32_bf16 v[72:75], v[166:169], v[210:213], v[72:75]
	v_mfma_f32_16x16x32_bf16 v[68:71], v[166:169], v[214:217], v[68:71]
	v_mfma_f32_16x16x32_bf16 v[64:67], v[166:169], v[218:221], v[64:67]
	s_add_u32 s60, s60, 0x80
	s_addc_u32 s61, s61, 0
	s_add_i32 s57, s57, 1
	s_branch .Lg8_top

.Lg9_top:
	s_xor_b32 s59, s59, 0x10000
	s_mov_b32 m0, s59
	s_add_u32 s46, s44, s12
	s_addc_u32 s47, s45, s13
	s_waitcnt lgkmcnt(0)
	s_waitcnt vmcnt(0)
	s_barrier
	global_load_lds_dwordx4 v178, s[46:47]
	ds_read_b128 v[142:145], v141
	ds_read_b128 v[146:149], v141 offset:2048
	ds_read_b128 v[150:153], v141 offset:4096
	ds_read_b128 v[154:157], v141 offset:6144
	ds_read_b128 v[174:177], v210 offset:32768
	ds_read_b128 v[182:185], v210 offset:34816
	ds_read_b128 v[186:189], v210 offset:36864
	ds_read_b128 v[190:193], v210 offset:38912
	v_mfma_f32_16x16x32_bf16 v[60:63], v[158:161], v[194:197], v[60:63]
	v_mfma_f32_16x16x32_bf16 v[56:59], v[158:161], v[198:201], v[56:59]
	s_add_u32 m0, s59, 0x2000
	s_add_u32 s46, s44, s14
	s_addc_u32 s47, s45, s15
	global_load_lds_dwordx4 v178, s[46:47]
	v_mfma_f32_16x16x32_bf16 v[52:55], v[158:161], v[202:205], v[52:55]
	v_mfma_f32_16x16x32_bf16 v[48:51], v[158:161], v[206:209], v[48:51]
	s_add_u32 m0, s59, 0x4000
	s_add_u32 s46, s44, s16
	s_addc_u32 s47, s45, s17
	global_load_lds_dwordx4 v178, s[46:47]
	v_mfma_f32_16x16x32_bf16 v[44:47], v[162:165], v[194:197], v[44:47]
	v_mfma_f32_16x16x32_bf16 v[32:35], v[162:165], v[198:201], v[32:35]
	s_add_u32 m0, s59, 0x6000
	s_add_u32 s46, s44, s18
	s_addc_u32 s47, s45, s19
	global_load_lds_dwordx4 v178, s[46:47]
	v_mfma_f32_16x16x32_bf16 v[28:31], v[162:165], v[202:205], v[28:31]
	v_mfma_f32_16x16x32_bf16 v[24:27], v[162:165], v[206:209], v[24:27]
	s_add_u32 m0, s59, 0x8000
	s_add_u32 s46, s44, s22
	s_addc_u32 s47, s45, s23
	global_load_lds_dwordx4 v179, s[46:47]
	v_mfma_f32_16x16x32_bf16 v[20:23], v[166:169], v[194:197], v[20:23]
	v_mfma_f32_16x16x32_bf16 v[16:19], v[166:169], v[198:201], v[16:19]
	s_add_u32 m0, s59, 0xa000
	s_add_u32 s46, s44, s36
	s_addc_u32 s47, s45, s37
	global_load_lds_dwordx4 v179, s[46:47]
	v_mfma_f32_16x16x32_bf16 v[12:15], v[166:169], v[202:205], v[12:15]
	v_mfma_f32_16x16x32_bf16 v[8:11], v[166:169], v[206:209], v[8:11]
	s_add_u32 m0, s59, 0xc000
	s_add_u32 s46, s44, s38
	s_addc_u32 s47, s45, s39
	global_load_lds_dwordx4 v179, s[46:47]
	v_mfma_f32_16x16x32_bf16 v[4:7], v[170:173], v[194:197], v[4:7]
	v_mfma_f32_16x16x32_bf16 v[0:3], v[170:173], v[198:201], v[0:3]
	s_add_u32 m0, s59, 0xe000
	s_add_u32 s46, s44, s40
	s_addc_u32 s47, s45, s41
	global_load_lds_dwordx4 v179, s[46:47]
	v_mfma_f32_16x16x32_bf16 v[40:43], v[170:173], v[202:205], v[40:43]
	v_mfma_f32_16x16x32_bf16 v[36:39], v[170:173], v[206:209], v[36:39]
.Lg9_entry:
	ds_read_b128 v[158:161], v141 offset:8192
	ds_read_b128 v[162:165], v141 offset:10240
	ds_read_b128 v[166:169], v141 offset:12288
	ds_read_b128 v[170:173], v141 offset:14336
	s_waitcnt lgkmcnt(4)
	v_mfma_f32_16x16x32_bf16 v[124:127], v[142:145], v[174:177], v[124:127]
	v_mfma_f32_16x16x32_bf16 v[120:123], v[142:145], v[182:185], v[120:123]
	v_mfma_f32_16x16x32_bf16 v[116:119], v[142:145], v[186:189], v[116:119]
	v_mfma_f32_16x16x32_bf16 v[112:115], v[142:145], v[190:193], v[112:115]
	v_mfma_f32_16x16x32_bf16 v[108:111], v[146:149], v[174:177], v[108:111]
	v_mfma_f32_16x16x32_bf16 v[104:107], v[146:149], v[182:185], v[104:107]
	v_mfma_f32_16x16x32_bf16 v[100:103], v[146:149], v[186:189], v[100:103]
	v_mfma_f32_16x16x32_bf16 v[96:99], v[146:149], v[190:193], v[96:99]
	v_mfma_f32_16x16x32_bf16 v[92:95], v[150:153], v[174:177], v[92:95]
	v_mfma_f32_16x16x32_bf16 v[88:91], v[150:153], v[182:185], v[88:91]
	v_mfma_f32_16x16x32_bf16 v[84:87], v[150:153], v[186:189], v[84:87]
	v_mfma_f32_16x16x32_bf16 v[80:83], v[150:153], v[190:193], v[80:83]
	v_mfma_f32_16x16x32_bf16 v[76:79], v[154:157], v[174:177], v[76:79]
	v_mfma_f32_16x16x32_bf16 v[72:75], v[154:157], v[182:185], v[72:75]
	v_mfma_f32_16x16x32_bf16 v[68:71], v[154:157], v[186:189], v[68:71]
	v_mfma_f32_16x16x32_bf16 v[64:67], v[154:157], v[190:193], v[64:67]
	ds_read_b128 v[142:145], v180
	ds_read_b128 v[146:149], v180 offset:2048
	ds_read_b128 v[150:153], v180 offset:4096
	ds_read_b128 v[154:157], v180 offset:6144
	ds_read_b128 v[194:197], v211 offset:32768
	ds_read_b128 v[198:201], v211 offset:34816
	ds_read_b128 v[202:205], v211 offset:36864
	ds_read_b128 v[206:209], v211 offset:38912
	s_waitcnt lgkmcnt(8)
	v_mfma_f32_16x16x32_bf16 v[60:63], v[158:161], v[174:177], v[60:63]
	v_mfma_f32_16x16x32_bf16 v[56:59], v[158:161], v[182:185], v[56:59]
	v_mfma_f32_16x16x32_bf16 v[52:55], v[158:161], v[186:189], v[52:55]
	v_mfma_f32_16x16x32_bf16 v[48:51], v[158:161], v[190:193], v[48:51]
	v_mfma_f32_16x16x32_bf16 v[44:47], v[162:165], v[174:177], v[44:47]
	v_mfma_f32_16x16x32_bf16 v[32:35], v[162:165], v[182:185], v[32:35]
	v_mfma_f32_16x16x32_bf16 v[28:31], v[162:165], v[186:189], v[28:31]
	v_mfma_f32_16x16x32_bf16 v[24:27], v[162:165], v[190:193], v[24:27]
	v_mfma_f32_16x16x32_bf16 v[20:23], v[166:169], v[174:177], v[20:23]
	v_mfma_f32_16x16x32_bf16 v[16:19], v[166:169], v[182:185], v[16:19]
	v_mfma_f32_16x16x32_bf16 v[12:15], v[166:169], v[186:189], v[12:15]
	v_mfma_f32_16x16x32_bf16 v[8:11], v[166:169], v[190:193], v[8:11]
	v_mfma_f32_16x16x32_bf16 v[4:7], v[170:173], v[174:177], v[4:7]
	v_mfma_f32_16x16x32_bf16 v[0:3], v[170:173], v[182:185], v[0:3]
	v_mfma_f32_16x16x32_bf16 v[40:43], v[170:173], v[186:189], v[40:43]
	v_mfma_f32_16x16x32_bf16 v[36:39], v[170:173], v[190:193], v[36:39]
	ds_read_b128 v[158:161], v180 offset:8192
	ds_read_b128 v[162:165], v180 offset:10240
	ds_read_b128 v[166:169], v180 offset:12288
	ds_read_b128 v[170:173], v180 offset:14336
	s_waitcnt lgkmcnt(4)
	v_mfma_f32_16x16x32_bf16 v[124:127], v[142:145], v[194:197], v[124:127]
	v_mfma_f32_16x16x32_bf16 v[120:123], v[142:145], v[198:201], v[120:123]
	v_mfma_f32_16x16x32_bf16 v[116:119], v[142:145], v[202:205], v[116:119]
	v_mfma_f32_16x16x32_bf16 v[112:115], v[142:145], v[206:209], v[112:115]
	v_mfma_f32_16x16x32_bf16 v[108:111], v[146:149], v[194:197], v[108:111]
	v_mfma_f32_16x16x32_bf16 v[104:107], v[146:149], v[198:201], v[104:107]
	v_mfma_f32_16x16x32_bf16 v[100:103], v[146:149], v[202:205], v[100:103]
	v_mfma_f32_16x16x32_bf16 v[96:99], v[146:149], v[206:209], v[96:99]
	v_mfma_f32_16x16x32_bf16 v[92:95], v[150:153], v[194:197], v[92:95]
	v_mfma_f32_16x16x32_bf16 v[88:91], v[150:153], v[198:201], v[88:91]
	v_mfma_f32_16x16x32_bf16 v[84:87], v[150:153], v[202:205], v[84:87]
	v_mfma_f32_16x16x32_bf16 v[80:83], v[150:153], v[206:209], v[80:83]
	v_mfma_f32_16x16x32_bf16 v[76:79], v[154:157], v[194:197], v[76:79]
	v_mfma_f32_16x16x32_bf16 v[72:75], v[154:157], v[198:201], v[72:75]
	v_mfma_f32_16x16x32_bf16 v[68:71], v[154:157], v[202:205], v[68:71]
	v_mfma_f32_16x16x32_bf16 v[64:67], v[154:157], v[206:209], v[64:67]
	s_add_u32 s44, s44, 0x80
	s_addc_u32 s45, s45, 0
	s_add_i32 s43, s43, 1
	s_cmp_lt_u32 s43, 31
	s_cbranch_scc0 .Lg9_last
	s_xor_b32 s59, s59, 0x10000
	s_mov_b32 m0, s59
	s_add_u32 s46, s44, s12
	s_addc_u32 s47, s45, s13
	s_waitcnt lgkmcnt(0)
	s_waitcnt vmcnt(0)
	s_barrier
	global_load_lds_dwordx4 v178, s[46:47]
	ds_read_b128 v[142:145], v212
	ds_read_b128 v[146:149], v212 offset:2048
	ds_read_b128 v[150:153], v212 offset:4096
	ds_read_b128 v[154:157], v212 offset:6144
	ds_read_b128 v[174:177], v214 offset:32768
	ds_read_b128 v[182:185], v214 offset:34816
	ds_read_b128 v[186:189], v214 offset:36864
	ds_read_b128 v[190:193], v214 offset:38912
	v_mfma_f32_16x16x32_bf16 v[60:63], v[158:161], v[194:197], v[60:63]
	v_mfma_f32_16x16x32_bf16 v[56:59], v[158:161], v[198:201], v[56:59]
	s_add_u32 m0, s59, 0x2000
	s_add_u32 s46, s44, s14
	s_addc_u32 s47, s45, s15
	global_load_lds_dwordx4 v178, s[46:47]
	v_mfma_f32_16x16x32_bf16 v[52:55], v[158:161], v[202:205], v[52:55]
	v_mfma_f32_16x16x32_bf16 v[48:51], v[158:161], v[206:209], v[48:51]
	s_add_u32 m0, s59, 0x4000
	s_add_u32 s46, s44, s16
	s_addc_u32 s47, s45, s17
	global_load_lds_dwordx4 v178, s[46:47]
	v_mfma_f32_16x16x32_bf16 v[44:47], v[162:165], v[194:197], v[44:47]
	v_mfma_f32_16x16x32_bf16 v[32:35], v[162:165], v[198:201], v[32:35]
	s_add_u32 m0, s59, 0x6000
	s_add_u32 s46, s44, s18
	s_addc_u32 s47, s45, s19
	global_load_lds_dwordx4 v178, s[46:47]
	v_mfma_f32_16x16x32_bf16 v[28:31], v[162:165], v[202:205], v[28:31]
	v_mfma_f32_16x16x32_bf16 v[24:27], v[162:165], v[206:209], v[24:27]
	s_add_u32 m0, s59, 0x8000
	s_add_u32 s46, s44, s22
	s_addc_u32 s47, s45, s23
	global_load_lds_dwordx4 v179, s[46:47]
	v_mfma_f32_16x16x32_bf16 v[20:23], v[166:169], v[194:197], v[20:23]
	v_mfma_f32_16x16x32_bf16 v[16:19], v[166:169], v[198:201], v[16:19]
	s_add_u32 m0, s59, 0xa000
	s_add_u32 s46, s44, s36
	s_addc_u32 s47, s45, s37
	global_load_lds_dwordx4 v179, s[46:47]
	v_mfma_f32_16x16x32_bf16 v[12:15], v[166:169], v[202:205], v[12:15]
	v_mfma_f32_16x16x32_bf16 v[8:11], v[166:169], v[206:209], v[8:11]
	s_add_u32 m0, s59, 0xc000
	s_add_u32 s46, s44, s38
	s_addc_u32 s47, s45, s39
	global_load_lds_dwordx4 v179, s[46:47]
	v_mfma_f32_16x16x32_bf16 v[4:7], v[170:173], v[194:197], v[4:7]
	v_mfma_f32_16x16x32_bf16 v[0:3], v[170:173], v[198:201], v[0:3]
	s_add_u32 m0, s59, 0xe000
	s_add_u32 s46, s44, s40
	s_addc_u32 s47, s45, s41
	global_load_lds_dwordx4 v179, s[46:47]
	v_mfma_f32_16x16x32_bf16 v[40:43], v[170:173], v[202:205], v[40:43]
	v_mfma_f32_16x16x32_bf16 v[36:39], v[170:173], v[206:209], v[36:39]
	ds_read_b128 v[158:161], v212 offset:8192
	ds_read_b128 v[162:165], v212 offset:10240
	ds_read_b128 v[166:169], v212 offset:12288
	ds_read_b128 v[170:173], v212 offset:14336
	s_waitcnt lgkmcnt(4)
	v_mfma_f32_16x16x32_bf16 v[124:127], v[142:145], v[174:177], v[124:127]
	v_mfma_f32_16x16x32_bf16 v[120:123], v[142:145], v[182:185], v[120:123]
	v_mfma_f32_16x16x32_bf16 v[116:119], v[142:145], v[186:189], v[116:119]
	v_mfma_f32_16x16x32_bf16 v[112:115], v[142:145], v[190:193], v[112:115]
	v_mfma_f32_16x16x32_bf16 v[108:111], v[146:149], v[174:177], v[108:111]
	v_mfma_f32_16x16x32_bf16 v[104:107], v[146:149], v[182:185], v[104:107]
	v_mfma_f32_16x16x32_bf16 v[100:103], v[146:149], v[186:189], v[100:103]
	v_mfma_f32_16x16x32_bf16 v[96:99], v[146:149], v[190:193], v[96:99]
	v_mfma_f32_16x16x32_bf16 v[92:95], v[150:153], v[174:177], v[92:95]
	v_mfma_f32_16x16x32_bf16 v[88:91], v[150:153], v[182:185], v[88:91]
	v_mfma_f32_16x16x32_bf16 v[84:87], v[150:153], v[186:189], v[84:87]
	v_mfma_f32_16x16x32_bf16 v[80:83], v[150:153], v[190:193], v[80:83]
	v_mfma_f32_16x16x32_bf16 v[76:79], v[154:157], v[174:177], v[76:79]
	v_mfma_f32_16x16x32_bf16 v[72:75], v[154:157], v[182:185], v[72:75]
	v_mfma_f32_16x16x32_bf16 v[68:71], v[154:157], v[186:189], v[68:71]
	v_mfma_f32_16x16x32_bf16 v[64:67], v[154:157], v[190:193], v[64:67]
	ds_read_b128 v[142:145], v213
	ds_read_b128 v[146:149], v213 offset:2048
	ds_read_b128 v[150:153], v213 offset:4096
	ds_read_b128 v[154:157], v213 offset:6144
	ds_read_b128 v[194:197], v215 offset:32768
	ds_read_b128 v[198:201], v215 offset:34816
	ds_read_b128 v[202:205], v215 offset:36864
	ds_read_b128 v[206:209], v215 offset:38912
	s_waitcnt lgkmcnt(8)
	v_mfma_f32_16x16x32_bf16 v[60:63], v[158:161], v[174:177], v[60:63]
	v_mfma_f32_16x16x32_bf16 v[56:59], v[158:161], v[182:185], v[56:59]
	v_mfma_f32_16x16x32_bf16 v[52:55], v[158:161], v[186:189], v[52:55]
	v_mfma_f32_16x16x32_bf16 v[48:51], v[158:161], v[190:193], v[48:51]
	v_mfma_f32_16x16x32_bf16 v[44:47], v[162:165], v[174:177], v[44:47]
	v_mfma_f32_16x16x32_bf16 v[32:35], v[162:165], v[182:185], v[32:35]
	v_mfma_f32_16x16x32_bf16 v[28:31], v[162:165], v[186:189], v[28:31]
	v_mfma_f32_16x16x32_bf16 v[24:27], v[162:165], v[190:193], v[24:27]
	v_mfma_f32_16x16x32_bf16 v[20:23], v[166:169], v[174:177], v[20:23]
	v_mfma_f32_16x16x32_bf16 v[16:19], v[166:169], v[182:185], v[16:19]
	v_mfma_f32_16x16x32_bf16 v[12:15], v[166:169], v[186:189], v[12:15]
	v_mfma_f32_16x16x32_bf16 v[8:11], v[166:169], v[190:193], v[8:11]
	v_mfma_f32_16x16x32_bf16 v[4:7], v[170:173], v[174:177], v[4:7]
	v_mfma_f32_16x16x32_bf16 v[0:3], v[170:173], v[182:185], v[0:3]
	v_mfma_f32_16x16x32_bf16 v[40:43], v[170:173], v[186:189], v[40:43]
	v_mfma_f32_16x16x32_bf16 v[36:39], v[170:173], v[190:193], v[36:39]
	ds_read_b128 v[158:161], v213 offset:8192
	ds_read_b128 v[162:165], v213 offset:10240
	ds_read_b128 v[166:169], v213 offset:12288
	ds_read_b128 v[170:173], v213 offset:14336
	s_waitcnt lgkmcnt(4)
	v_mfma_f32_16x16x32_bf16 v[124:127], v[142:145], v[194:197], v[124:127]
	v_mfma_f32_16x16x32_bf16 v[120:123], v[142:145], v[198:201], v[120:123]
	v_mfma_f32_16x16x32_bf16 v[116:119], v[142:145], v[202:205], v[116:119]
	v_mfma_f32_16x16x32_bf16 v[112:115], v[142:145], v[206:209], v[112:115]
	v_mfma_f32_16x16x32_bf16 v[108:111], v[146:149], v[194:197], v[108:111]
	v_mfma_f32_16x16x32_bf16 v[104:107], v[146:149], v[198:201], v[104:107]
	v_mfma_f32_16x16x32_bf16 v[100:103], v[146:149], v[202:205], v[100:103]
	v_mfma_f32_16x16x32_bf16 v[96:99], v[146:149], v[206:209], v[96:99]
	v_mfma_f32_16x16x32_bf16 v[92:95], v[150:153], v[194:197], v[92:95]
	v_mfma_f32_16x16x32_bf16 v[88:91], v[150:153], v[198:201], v[88:91]
	v_mfma_f32_16x16x32_bf16 v[84:87], v[150:153], v[202:205], v[84:87]
	v_mfma_f32_16x16x32_bf16 v[80:83], v[150:153], v[206:209], v[80:83]
	v_mfma_f32_16x16x32_bf16 v[76:79], v[154:157], v[194:197], v[76:79]
	v_mfma_f32_16x16x32_bf16 v[72:75], v[154:157], v[198:201], v[72:75]
	v_mfma_f32_16x16x32_bf16 v[68:71], v[154:157], v[202:205], v[68:71]
	v_mfma_f32_16x16x32_bf16 v[64:67], v[154:157], v[206:209], v[64:67]
	s_add_u32 s44, s44, 0x80
	s_addc_u32 s45, s45, 0
	s_add_i32 s43, s43, 1
	s_branch .Lg9_top

.Lg10_top:
	s_xor_b32 s57, s57, 0x10000
	s_mov_b32 m0, s57
	s_add_u32 s46, s44, s14
	s_addc_u32 s47, s45, s15
	s_waitcnt lgkmcnt(0)
	s_waitcnt vmcnt(0)
	s_barrier
	global_load_lds_dwordx4 v144, s[46:47]
	ds_read_b128 v[156:159], v143
	ds_read_b128 v[160:163], v143 offset:2048
	ds_read_b128 v[164:167], v143 offset:4096
	ds_read_b128 v[168:171], v143 offset:6144
	ds_read_b128 v[190:193], v180 offset:32768
	ds_read_b128 v[194:197], v180 offset:34816
	ds_read_b128 v[198:201], v180 offset:36864
	ds_read_b128 v[202:205], v180 offset:38912
	v_mfma_f32_16x16x32_bf16 v[60:63], v[172:175], v[206:209], v[60:63]
	v_mfma_f32_16x16x32_bf16 v[52:55], v[172:175], v[210:213], v[52:55]
	s_add_u32 m0, s57, 0x2000
	s_add_u32 s46, s44, s16
	s_addc_u32 s47, s45, s17
	global_load_lds_dwordx4 v144, s[46:47]
	v_mfma_f32_16x16x32_bf16 v[56:59], v[172:175], v[214:217], v[56:59]
	v_mfma_f32_16x16x32_bf16 v[48:51], v[172:175], v[218:221], v[48:51]
	s_add_u32 m0, s57, 0x4000
	s_add_u32 s46, s44, s18
	s_addc_u32 s47, s45, s19
	global_load_lds_dwordx4 v144, s[46:47]
	v_mfma_f32_16x16x32_bf16 v[44:47], v[176:179], v[206:209], v[44:47]
	v_mfma_f32_16x16x32_bf16 v[36:39], v[176:179], v[210:213], v[36:39]
	s_add_u32 m0, s57, 0x6000
	s_add_u32 s46, s44, s22
	s_addc_u32 s47, s45, s23
	global_load_lds_dwordx4 v144, s[46:47]
	v_mfma_f32_16x16x32_bf16 v[40:43], v[176:179], v[214:217], v[40:43]
	v_mfma_f32_16x16x32_bf16 v[32:35], v[176:179], v[218:221], v[32:35]
	s_add_u32 m0, s57, 0x8000
	s_add_u32 s46, s44, s30
	s_addc_u32 s47, s45, s31
	global_load_lds_dwordx4 v145, s[46:47]
	v_mfma_f32_16x16x32_bf16 v[28:31], v[182:185], v[206:209], v[28:31]
	v_mfma_f32_16x16x32_bf16 v[16:19], v[182:185], v[210:213], v[16:19]
	s_add_u32 m0, s57, 0xa000
	s_add_u32 s46, s44, s36
	s_addc_u32 s47, s45, s37
	global_load_lds_dwordx4 v145, s[46:47]
	v_mfma_f32_16x16x32_bf16 v[24:27], v[182:185], v[214:217], v[24:27]
	v_mfma_f32_16x16x32_bf16 v[12:15], v[182:185], v[218:221], v[12:15]
	s_add_u32 m0, s57, 0xc000
	s_add_u32 s46, s44, s38
	s_addc_u32 s47, s45, s39
	global_load_lds_dwordx4 v145, s[46:47]
	v_mfma_f32_16x16x32_bf16 v[4:7], v[186:189], v[206:209], v[4:7]
	v_mfma_f32_16x16x32_bf16 v[0:3], v[186:189], v[210:213], v[0:3]
	s_add_u32 m0, s57, 0xe000
	s_add_u32 s46, s44, s40
	s_addc_u32 s47, s45, s41
	global_load_lds_dwordx4 v145, s[46:47]
	v_mfma_f32_16x16x32_bf16 v[20:23], v[186:189], v[214:217], v[20:23]
	v_mfma_f32_16x16x32_bf16 v[8:11], v[186:189], v[218:221], v[8:11]
.Lg10_entry:
	ds_read_b128 v[172:175], v143 offset:8192
	ds_read_b128 v[176:179], v143 offset:10240
	ds_read_b128 v[182:185], v143 offset:12288
	ds_read_b128 v[186:189], v143 offset:14336
	s_waitcnt lgkmcnt(4)
	v_mfma_f32_16x16x32_bf16 v[124:127], v[156:159], v[190:193], v[124:127]
	v_mfma_f32_16x16x32_bf16 v[116:119], v[156:159], v[194:197], v[116:119]
	v_mfma_f32_16x16x32_bf16 v[120:123], v[156:159], v[198:201], v[120:123]
	v_mfma_f32_16x16x32_bf16 v[112:115], v[156:159], v[202:205], v[112:115]
	v_mfma_f32_16x16x32_bf16 v[108:111], v[160:163], v[190:193], v[108:111]
	v_mfma_f32_16x16x32_bf16 v[100:103], v[160:163], v[194:197], v[100:103]
	v_mfma_f32_16x16x32_bf16 v[104:107], v[160:163], v[198:201], v[104:107]
	v_mfma_f32_16x16x32_bf16 v[96:99], v[160:163], v[202:205], v[96:99]
	v_mfma_f32_16x16x32_bf16 v[92:95], v[164:167], v[190:193], v[92:95]
	v_mfma_f32_16x16x32_bf16 v[84:87], v[164:167], v[194:197], v[84:87]
	v_mfma_f32_16x16x32_bf16 v[88:91], v[164:167], v[198:201], v[88:91]
	v_mfma_f32_16x16x32_bf16 v[80:83], v[164:167], v[202:205], v[80:83]
	v_mfma_f32_16x16x32_bf16 v[76:79], v[168:171], v[190:193], v[76:79]
	v_mfma_f32_16x16x32_bf16 v[68:71], v[168:171], v[194:197], v[68:71]
	v_mfma_f32_16x16x32_bf16 v[72:75], v[168:171], v[198:201], v[72:75]
	v_mfma_f32_16x16x32_bf16 v[64:67], v[168:171], v[202:205], v[64:67]
	ds_read_b128 v[156:159], v155
	ds_read_b128 v[160:163], v155 offset:2048
	ds_read_b128 v[164:167], v155 offset:4096
	ds_read_b128 v[168:171], v155 offset:6144
	ds_read_b128 v[206:209], v222 offset:32768
	ds_read_b128 v[210:213], v222 offset:34816
	ds_read_b128 v[214:217], v222 offset:36864
	ds_read_b128 v[218:221], v222 offset:38912
	s_waitcnt lgkmcnt(8)
	v_mfma_f32_16x16x32_bf16 v[60:63], v[172:175], v[190:193], v[60:63]
	v_mfma_f32_16x16x32_bf16 v[52:55], v[172:175], v[194:197], v[52:55]
	v_mfma_f32_16x16x32_bf16 v[56:59], v[172:175], v[198:201], v[56:59]
	v_mfma_f32_16x16x32_bf16 v[48:51], v[172:175], v[202:205], v[48:51]
	v_mfma_f32_16x16x32_bf16 v[44:47], v[176:179], v[190:193], v[44:47]
	v_mfma_f32_16x16x32_bf16 v[36:39], v[176:179], v[194:197], v[36:39]
	v_mfma_f32_16x16x32_bf16 v[40:43], v[176:179], v[198:201], v[40:43]
	v_mfma_f32_16x16x32_bf16 v[32:35], v[176:179], v[202:205], v[32:35]
	v_mfma_f32_16x16x32_bf16 v[28:31], v[182:185], v[190:193], v[28:31]
	v_mfma_f32_16x16x32_bf16 v[16:19], v[182:185], v[194:197], v[16:19]
	v_mfma_f32_16x16x32_bf16 v[24:27], v[182:185], v[198:201], v[24:27]
	v_mfma_f32_16x16x32_bf16 v[12:15], v[182:185], v[202:205], v[12:15]
	v_mfma_f32_16x16x32_bf16 v[4:7], v[186:189], v[190:193], v[4:7]
	v_mfma_f32_16x16x32_bf16 v[0:3], v[186:189], v[194:197], v[0:3]
	v_mfma_f32_16x16x32_bf16 v[20:23], v[186:189], v[198:201], v[20:23]
	v_mfma_f32_16x16x32_bf16 v[8:11], v[186:189], v[202:205], v[8:11]
	ds_read_b128 v[172:175], v155 offset:8192
	ds_read_b128 v[176:179], v155 offset:10240
	ds_read_b128 v[182:185], v155 offset:12288
	ds_read_b128 v[186:189], v155 offset:14336
	s_waitcnt lgkmcnt(4)
	v_mfma_f32_16x16x32_bf16 v[124:127], v[156:159], v[206:209], v[124:127]
	v_mfma_f32_16x16x32_bf16 v[116:119], v[156:159], v[210:213], v[116:119]
	v_mfma_f32_16x16x32_bf16 v[120:123], v[156:159], v[214:217], v[120:123]
	v_mfma_f32_16x16x32_bf16 v[112:115], v[156:159], v[218:221], v[112:115]
	v_mfma_f32_16x16x32_bf16 v[108:111], v[160:163], v[206:209], v[108:111]
	v_mfma_f32_16x16x32_bf16 v[100:103], v[160:163], v[210:213], v[100:103]
	v_mfma_f32_16x16x32_bf16 v[104:107], v[160:163], v[214:217], v[104:107]
	v_mfma_f32_16x16x32_bf16 v[96:99], v[160:163], v[218:221], v[96:99]
	v_mfma_f32_16x16x32_bf16 v[92:95], v[164:167], v[206:209], v[92:95]
	v_mfma_f32_16x16x32_bf16 v[84:87], v[164:167], v[210:213], v[84:87]
	v_mfma_f32_16x16x32_bf16 v[88:91], v[164:167], v[214:217], v[88:91]
	v_mfma_f32_16x16x32_bf16 v[80:83], v[164:167], v[218:221], v[80:83]
	v_mfma_f32_16x16x32_bf16 v[76:79], v[168:171], v[206:209], v[76:79]
	v_mfma_f32_16x16x32_bf16 v[68:71], v[168:171], v[210:213], v[68:71]
	v_mfma_f32_16x16x32_bf16 v[72:75], v[168:171], v[214:217], v[72:75]
	v_mfma_f32_16x16x32_bf16 v[64:67], v[168:171], v[218:221], v[64:67]
	s_add_u32 s44, s44, 0x80
	s_addc_u32 s45, s45, 0
	s_add_i32 s43, s43, 1
	s_cmp_lt_u32 s43, 15
	s_cbranch_scc0 .Lg10_last
	s_xor_b32 s57, s57, 0x10000
	s_mov_b32 m0, s57
	s_add_u32 s46, s44, s14
	s_addc_u32 s47, s45, s15
	s_waitcnt lgkmcnt(0)
	s_waitcnt vmcnt(0)
	s_barrier
	global_load_lds_dwordx4 v144, s[46:47]
	ds_read_b128 v[156:159], v223
	ds_read_b128 v[160:163], v223 offset:2048
	ds_read_b128 v[164:167], v223 offset:4096
	ds_read_b128 v[168:171], v223 offset:6144
	ds_read_b128 v[190:193], v225 offset:32768
	ds_read_b128 v[194:197], v225 offset:34816
	ds_read_b128 v[198:201], v225 offset:36864
	ds_read_b128 v[202:205], v225 offset:38912
	v_mfma_f32_16x16x32_bf16 v[60:63], v[172:175], v[206:209], v[60:63]
	v_mfma_f32_16x16x32_bf16 v[52:55], v[172:175], v[210:213], v[52:55]
	s_add_u32 m0, s57, 0x2000
	s_add_u32 s46, s44, s16
	s_addc_u32 s47, s45, s17
	global_load_lds_dwordx4 v144, s[46:47]
	v_mfma_f32_16x16x32_bf16 v[56:59], v[172:175], v[214:217], v[56:59]
	v_mfma_f32_16x16x32_bf16 v[48:51], v[172:175], v[218:221], v[48:51]
	s_add_u32 m0, s57, 0x4000
	s_add_u32 s46, s44, s18
	s_addc_u32 s47, s45, s19
	global_load_lds_dwordx4 v144, s[46:47]
	v_mfma_f32_16x16x32_bf16 v[44:47], v[176:179], v[206:209], v[44:47]
	v_mfma_f32_16x16x32_bf16 v[36:39], v[176:179], v[210:213], v[36:39]
	s_add_u32 m0, s57, 0x6000
	s_add_u32 s46, s44, s22
	s_addc_u32 s47, s45, s23
	global_load_lds_dwordx4 v144, s[46:47]
	v_mfma_f32_16x16x32_bf16 v[40:43], v[176:179], v[214:217], v[40:43]
	v_mfma_f32_16x16x32_bf16 v[32:35], v[176:179], v[218:221], v[32:35]
	s_add_u32 m0, s57, 0x8000
	s_add_u32 s46, s44, s30
	s_addc_u32 s47, s45, s31
	global_load_lds_dwordx4 v145, s[46:47]
	v_mfma_f32_16x16x32_bf16 v[28:31], v[182:185], v[206:209], v[28:31]
	v_mfma_f32_16x16x32_bf16 v[16:19], v[182:185], v[210:213], v[16:19]
	s_add_u32 m0, s57, 0xa000
	s_add_u32 s46, s44, s36
	s_addc_u32 s47, s45, s37
	global_load_lds_dwordx4 v145, s[46:47]
	v_mfma_f32_16x16x32_bf16 v[24:27], v[182:185], v[214:217], v[24:27]
	v_mfma_f32_16x16x32_bf16 v[12:15], v[182:185], v[218:221], v[12:15]
	s_add_u32 m0, s57, 0xc000
	s_add_u32 s46, s44, s38
	s_addc_u32 s47, s45, s39
	global_load_lds_dwordx4 v145, s[46:47]
	v_mfma_f32_16x16x32_bf16 v[4:7], v[186:189], v[206:209], v[4:7]
	v_mfma_f32_16x16x32_bf16 v[0:3], v[186:189], v[210:213], v[0:3]
	s_add_u32 m0, s57, 0xe000
	s_add_u32 s46, s44, s40
	s_addc_u32 s47, s45, s41
	global_load_lds_dwordx4 v145, s[46:47]
	v_mfma_f32_16x16x32_bf16 v[20:23], v[186:189], v[214:217], v[20:23]
	v_mfma_f32_16x16x32_bf16 v[8:11], v[186:189], v[218:221], v[8:11]
	ds_read_b128 v[172:175], v223 offset:8192
	ds_read_b128 v[176:179], v223 offset:10240
	ds_read_b128 v[182:185], v223 offset:12288
	ds_read_b128 v[186:189], v223 offset:14336
	s_waitcnt lgkmcnt(4)
	v_mfma_f32_16x16x32_bf16 v[124:127], v[156:159], v[190:193], v[124:127]
	v_mfma_f32_16x16x32_bf16 v[116:119], v[156:159], v[194:197], v[116:119]
	v_mfma_f32_16x16x32_bf16 v[120:123], v[156:159], v[198:201], v[120:123]
	v_mfma_f32_16x16x32_bf16 v[112:115], v[156:159], v[202:205], v[112:115]
	v_mfma_f32_16x16x32_bf16 v[108:111], v[160:163], v[190:193], v[108:111]
	v_mfma_f32_16x16x32_bf16 v[100:103], v[160:163], v[194:197], v[100:103]
	v_mfma_f32_16x16x32_bf16 v[104:107], v[160:163], v[198:201], v[104:107]
	v_mfma_f32_16x16x32_bf16 v[96:99], v[160:163], v[202:205], v[96:99]
	v_mfma_f32_16x16x32_bf16 v[92:95], v[164:167], v[190:193], v[92:95]
	v_mfma_f32_16x16x32_bf16 v[84:87], v[164:167], v[194:197], v[84:87]
	v_mfma_f32_16x16x32_bf16 v[88:91], v[164:167], v[198:201], v[88:91]
	v_mfma_f32_16x16x32_bf16 v[80:83], v[164:167], v[202:205], v[80:83]
	v_mfma_f32_16x16x32_bf16 v[76:79], v[168:171], v[190:193], v[76:79]
	v_mfma_f32_16x16x32_bf16 v[68:71], v[168:171], v[194:197], v[68:71]
	v_mfma_f32_16x16x32_bf16 v[72:75], v[168:171], v[198:201], v[72:75]
	v_mfma_f32_16x16x32_bf16 v[64:67], v[168:171], v[202:205], v[64:67]
	ds_read_b128 v[156:159], v224
	ds_read_b128 v[160:163], v224 offset:2048
	ds_read_b128 v[164:167], v224 offset:4096
	ds_read_b128 v[168:171], v224 offset:6144
	ds_read_b128 v[206:209], v226 offset:32768
	ds_read_b128 v[210:213], v226 offset:34816
	ds_read_b128 v[214:217], v226 offset:36864
	ds_read_b128 v[218:221], v226 offset:38912
	s_waitcnt lgkmcnt(8)
	v_mfma_f32_16x16x32_bf16 v[60:63], v[172:175], v[190:193], v[60:63]
	v_mfma_f32_16x16x32_bf16 v[52:55], v[172:175], v[194:197], v[52:55]
	v_mfma_f32_16x16x32_bf16 v[56:59], v[172:175], v[198:201], v[56:59]
	v_mfma_f32_16x16x32_bf16 v[48:51], v[172:175], v[202:205], v[48:51]
	v_mfma_f32_16x16x32_bf16 v[44:47], v[176:179], v[190:193], v[44:47]
	v_mfma_f32_16x16x32_bf16 v[36:39], v[176:179], v[194:197], v[36:39]
	v_mfma_f32_16x16x32_bf16 v[40:43], v[176:179], v[198:201], v[40:43]
	v_mfma_f32_16x16x32_bf16 v[32:35], v[176:179], v[202:205], v[32:35]
	v_mfma_f32_16x16x32_bf16 v[28:31], v[182:185], v[190:193], v[28:31]
	v_mfma_f32_16x16x32_bf16 v[16:19], v[182:185], v[194:197], v[16:19]
	v_mfma_f32_16x16x32_bf16 v[24:27], v[182:185], v[198:201], v[24:27]
	v_mfma_f32_16x16x32_bf16 v[12:15], v[182:185], v[202:205], v[12:15]
	v_mfma_f32_16x16x32_bf16 v[4:7], v[186:189], v[190:193], v[4:7]
	v_mfma_f32_16x16x32_bf16 v[0:3], v[186:189], v[194:197], v[0:3]
	v_mfma_f32_16x16x32_bf16 v[20:23], v[186:189], v[198:201], v[20:23]
	v_mfma_f32_16x16x32_bf16 v[8:11], v[186:189], v[202:205], v[8:11]
	ds_read_b128 v[172:175], v224 offset:8192
	ds_read_b128 v[176:179], v224 offset:10240
	ds_read_b128 v[182:185], v224 offset:12288
	ds_read_b128 v[186:189], v224 offset:14336
	s_waitcnt lgkmcnt(4)
	v_mfma_f32_16x16x32_bf16 v[124:127], v[156:159], v[206:209], v[124:127]
	v_mfma_f32_16x16x32_bf16 v[116:119], v[156:159], v[210:213], v[116:119]
	v_mfma_f32_16x16x32_bf16 v[120:123], v[156:159], v[214:217], v[120:123]
	v_mfma_f32_16x16x32_bf16 v[112:115], v[156:159], v[218:221], v[112:115]
	v_mfma_f32_16x16x32_bf16 v[108:111], v[160:163], v[206:209], v[108:111]
	v_mfma_f32_16x16x32_bf16 v[100:103], v[160:163], v[210:213], v[100:103]
	v_mfma_f32_16x16x32_bf16 v[104:107], v[160:163], v[214:217], v[104:107]
	v_mfma_f32_16x16x32_bf16 v[96:99], v[160:163], v[218:221], v[96:99]
	v_mfma_f32_16x16x32_bf16 v[92:95], v[164:167], v[206:209], v[92:95]
	v_mfma_f32_16x16x32_bf16 v[84:87], v[164:167], v[210:213], v[84:87]
	v_mfma_f32_16x16x32_bf16 v[88:91], v[164:167], v[214:217], v[88:91]
	v_mfma_f32_16x16x32_bf16 v[80:83], v[164:167], v[218:221], v[80:83]
	v_mfma_f32_16x16x32_bf16 v[76:79], v[168:171], v[206:209], v[76:79]
	v_mfma_f32_16x16x32_bf16 v[68:71], v[168:171], v[210:213], v[68:71]
	v_mfma_f32_16x16x32_bf16 v[72:75], v[168:171], v[214:217], v[72:75]
	v_mfma_f32_16x16x32_bf16 v[64:67], v[168:171], v[218:221], v[64:67]
	s_add_u32 s44, s44, 0x80
	s_addc_u32 s45, s45, 0
	s_add_i32 s43, s43, 1
	s_branch .Lg10_top

.Lg11_top:
	s_xor_b32 s45, s45, 0x10000
	s_mov_b32 m0, s45
	s_add_u32 s38, s36, s12
	s_addc_u32 s39, s37, s13
	s_waitcnt lgkmcnt(0)
	s_waitcnt vmcnt(0)
	s_barrier
	global_load_lds_dwordx4 v178, s[38:39]
	ds_read_b128 v[142:145], v141
	ds_read_b128 v[146:149], v141 offset:2048
	ds_read_b128 v[150:153], v141 offset:4096
	ds_read_b128 v[154:157], v141 offset:6144
	ds_read_b128 v[174:177], v210 offset:32768
	ds_read_b128 v[182:185], v210 offset:34816
	ds_read_b128 v[186:189], v210 offset:36864
	ds_read_b128 v[190:193], v210 offset:38912
	v_mfma_f32_16x16x32_bf16 v[60:63], v[158:161], v[194:197], v[60:63]
	v_mfma_f32_16x16x32_bf16 v[56:59], v[158:161], v[198:201], v[56:59]
	s_add_u32 m0, s45, 0x2000
	s_add_u32 s38, s36, s14
	s_addc_u32 s39, s37, s15
	global_load_lds_dwordx4 v178, s[38:39]
	v_mfma_f32_16x16x32_bf16 v[52:55], v[158:161], v[202:205], v[52:55]
	v_mfma_f32_16x16x32_bf16 v[48:51], v[158:161], v[206:209], v[48:51]
	s_add_u32 m0, s45, 0x4000
	s_add_u32 s38, s36, s16
	s_addc_u32 s39, s37, s17
	global_load_lds_dwordx4 v178, s[38:39]
	v_mfma_f32_16x16x32_bf16 v[44:47], v[162:165], v[194:197], v[44:47]
	v_mfma_f32_16x16x32_bf16 v[32:35], v[162:165], v[198:201], v[32:35]
	s_add_u32 m0, s45, 0x6000
	s_add_u32 s38, s36, s18
	s_addc_u32 s39, s37, s19
	global_load_lds_dwordx4 v178, s[38:39]
	v_mfma_f32_16x16x32_bf16 v[28:31], v[162:165], v[202:205], v[28:31]
	v_mfma_f32_16x16x32_bf16 v[24:27], v[162:165], v[206:209], v[24:27]
	s_add_u32 m0, s45, 0x8000
	s_add_u32 s38, s36, s22
	s_addc_u32 s39, s37, s23
	global_load_lds_dwordx4 v179, s[38:39]
	v_mfma_f32_16x16x32_bf16 v[20:23], v[166:169], v[194:197], v[20:23]
	v_mfma_f32_16x16x32_bf16 v[16:19], v[166:169], v[198:201], v[16:19]
	s_add_u32 m0, s45, 0xa000
	s_add_u32 s38, s36, s24
	s_addc_u32 s39, s37, s25
	global_load_lds_dwordx4 v179, s[38:39]
	v_mfma_f32_16x16x32_bf16 v[12:15], v[166:169], v[202:205], v[12:15]
	v_mfma_f32_16x16x32_bf16 v[8:11], v[166:169], v[206:209], v[8:11]
	s_add_u32 m0, s45, 0xc000
	s_add_u32 s38, s36, s26
	s_addc_u32 s39, s37, s27
	global_load_lds_dwordx4 v179, s[38:39]
	v_mfma_f32_16x16x32_bf16 v[4:7], v[170:173], v[194:197], v[4:7]
	v_mfma_f32_16x16x32_bf16 v[0:3], v[170:173], v[198:201], v[0:3]
	s_add_u32 m0, s45, 0xe000
	s_add_u32 s38, s36, s28
	s_addc_u32 s39, s37, s29
	global_load_lds_dwordx4 v179, s[38:39]
	v_mfma_f32_16x16x32_bf16 v[40:43], v[170:173], v[202:205], v[40:43]
	v_mfma_f32_16x16x32_bf16 v[36:39], v[170:173], v[206:209], v[36:39]
.Lg11_entry:
	ds_read_b128 v[158:161], v141 offset:8192
	ds_read_b128 v[162:165], v141 offset:10240
	ds_read_b128 v[166:169], v141 offset:12288
	ds_read_b128 v[170:173], v141 offset:14336
	s_waitcnt lgkmcnt(4)
	v_mfma_f32_16x16x32_bf16 v[124:127], v[142:145], v[174:177], v[124:127]
	v_mfma_f32_16x16x32_bf16 v[120:123], v[142:145], v[182:185], v[120:123]
	v_mfma_f32_16x16x32_bf16 v[116:119], v[142:145], v[186:189], v[116:119]
	v_mfma_f32_16x16x32_bf16 v[112:115], v[142:145], v[190:193], v[112:115]
	v_mfma_f32_16x16x32_bf16 v[108:111], v[146:149], v[174:177], v[108:111]
	v_mfma_f32_16x16x32_bf16 v[104:107], v[146:149], v[182:185], v[104:107]
	v_mfma_f32_16x16x32_bf16 v[100:103], v[146:149], v[186:189], v[100:103]
	v_mfma_f32_16x16x32_bf16 v[96:99], v[146:149], v[190:193], v[96:99]
	v_mfma_f32_16x16x32_bf16 v[92:95], v[150:153], v[174:177], v[92:95]
	v_mfma_f32_16x16x32_bf16 v[88:91], v[150:153], v[182:185], v[88:91]
	v_mfma_f32_16x16x32_bf16 v[84:87], v[150:153], v[186:189], v[84:87]
	v_mfma_f32_16x16x32_bf16 v[80:83], v[150:153], v[190:193], v[80:83]
	v_mfma_f32_16x16x32_bf16 v[76:79], v[154:157], v[174:177], v[76:79]
	v_mfma_f32_16x16x32_bf16 v[72:75], v[154:157], v[182:185], v[72:75]
	v_mfma_f32_16x16x32_bf16 v[68:71], v[154:157], v[186:189], v[68:71]
	v_mfma_f32_16x16x32_bf16 v[64:67], v[154:157], v[190:193], v[64:67]
	ds_read_b128 v[142:145], v180
	ds_read_b128 v[146:149], v180 offset:2048
	ds_read_b128 v[150:153], v180 offset:4096
	ds_read_b128 v[154:157], v180 offset:6144
	ds_read_b128 v[194:197], v211 offset:32768
	ds_read_b128 v[198:201], v211 offset:34816
	ds_read_b128 v[202:205], v211 offset:36864
	ds_read_b128 v[206:209], v211 offset:38912
	s_waitcnt lgkmcnt(8)
	v_mfma_f32_16x16x32_bf16 v[60:63], v[158:161], v[174:177], v[60:63]
	v_mfma_f32_16x16x32_bf16 v[56:59], v[158:161], v[182:185], v[56:59]
	v_mfma_f32_16x16x32_bf16 v[52:55], v[158:161], v[186:189], v[52:55]
	v_mfma_f32_16x16x32_bf16 v[48:51], v[158:161], v[190:193], v[48:51]
	v_mfma_f32_16x16x32_bf16 v[44:47], v[162:165], v[174:177], v[44:47]
	v_mfma_f32_16x16x32_bf16 v[32:35], v[162:165], v[182:185], v[32:35]
	v_mfma_f32_16x16x32_bf16 v[28:31], v[162:165], v[186:189], v[28:31]
	v_mfma_f32_16x16x32_bf16 v[24:27], v[162:165], v[190:193], v[24:27]
	v_mfma_f32_16x16x32_bf16 v[20:23], v[166:169], v[174:177], v[20:23]
	v_mfma_f32_16x16x32_bf16 v[16:19], v[166:169], v[182:185], v[16:19]
	v_mfma_f32_16x16x32_bf16 v[12:15], v[166:169], v[186:189], v[12:15]
	v_mfma_f32_16x16x32_bf16 v[8:11], v[166:169], v[190:193], v[8:11]
	v_mfma_f32_16x16x32_bf16 v[4:7], v[170:173], v[174:177], v[4:7]
	v_mfma_f32_16x16x32_bf16 v[0:3], v[170:173], v[182:185], v[0:3]
	v_mfma_f32_16x16x32_bf16 v[40:43], v[170:173], v[186:189], v[40:43]
	v_mfma_f32_16x16x32_bf16 v[36:39], v[170:173], v[190:193], v[36:39]
	ds_read_b128 v[158:161], v180 offset:8192
	ds_read_b128 v[162:165], v180 offset:10240
	ds_read_b128 v[166:169], v180 offset:12288
	ds_read_b128 v[170:173], v180 offset:14336
	s_waitcnt lgkmcnt(4)
	v_mfma_f32_16x16x32_bf16 v[124:127], v[142:145], v[194:197], v[124:127]
	v_mfma_f32_16x16x32_bf16 v[120:123], v[142:145], v[198:201], v[120:123]
	v_mfma_f32_16x16x32_bf16 v[116:119], v[142:145], v[202:205], v[116:119]
	v_mfma_f32_16x16x32_bf16 v[112:115], v[142:145], v[206:209], v[112:115]
	v_mfma_f32_16x16x32_bf16 v[108:111], v[146:149], v[194:197], v[108:111]
	v_mfma_f32_16x16x32_bf16 v[104:107], v[146:149], v[198:201], v[104:107]
	v_mfma_f32_16x16x32_bf16 v[100:103], v[146:149], v[202:205], v[100:103]
	v_mfma_f32_16x16x32_bf16 v[96:99], v[146:149], v[206:209], v[96:99]
	v_mfma_f32_16x16x32_bf16 v[92:95], v[150:153], v[194:197], v[92:95]
	v_mfma_f32_16x16x32_bf16 v[88:91], v[150:153], v[198:201], v[88:91]
	v_mfma_f32_16x16x32_bf16 v[84:87], v[150:153], v[202:205], v[84:87]
	v_mfma_f32_16x16x32_bf16 v[80:83], v[150:153], v[206:209], v[80:83]
	v_mfma_f32_16x16x32_bf16 v[76:79], v[154:157], v[194:197], v[76:79]
	v_mfma_f32_16x16x32_bf16 v[72:75], v[154:157], v[198:201], v[72:75]
	v_mfma_f32_16x16x32_bf16 v[68:71], v[154:157], v[202:205], v[68:71]
	v_mfma_f32_16x16x32_bf16 v[64:67], v[154:157], v[206:209], v[64:67]
	s_add_u32 s36, s36, 0x80
	s_addc_u32 s37, s37, 0
	s_add_i32 s31, s31, 1
	s_cmp_lt_u32 s31, 31
	s_cbranch_scc0 .Lg11_last
	s_xor_b32 s45, s45, 0x10000
	s_mov_b32 m0, s45
	s_add_u32 s38, s36, s12
	s_addc_u32 s39, s37, s13
	s_waitcnt lgkmcnt(0)
	s_waitcnt vmcnt(0)
	s_barrier
	global_load_lds_dwordx4 v178, s[38:39]
	ds_read_b128 v[142:145], v212
	ds_read_b128 v[146:149], v212 offset:2048
	ds_read_b128 v[150:153], v212 offset:4096
	ds_read_b128 v[154:157], v212 offset:6144
	ds_read_b128 v[174:177], v214 offset:32768
	ds_read_b128 v[182:185], v214 offset:34816
	ds_read_b128 v[186:189], v214 offset:36864
	ds_read_b128 v[190:193], v214 offset:38912
	v_mfma_f32_16x16x32_bf16 v[60:63], v[158:161], v[194:197], v[60:63]
	v_mfma_f32_16x16x32_bf16 v[56:59], v[158:161], v[198:201], v[56:59]
	s_add_u32 m0, s45, 0x2000
	s_add_u32 s38, s36, s14
	s_addc_u32 s39, s37, s15
	global_load_lds_dwordx4 v178, s[38:39]
	v_mfma_f32_16x16x32_bf16 v[52:55], v[158:161], v[202:205], v[52:55]
	v_mfma_f32_16x16x32_bf16 v[48:51], v[158:161], v[206:209], v[48:51]
	s_add_u32 m0, s45, 0x4000
	s_add_u32 s38, s36, s16
	s_addc_u32 s39, s37, s17
	global_load_lds_dwordx4 v178, s[38:39]
	v_mfma_f32_16x16x32_bf16 v[44:47], v[162:165], v[194:197], v[44:47]
	v_mfma_f32_16x16x32_bf16 v[32:35], v[162:165], v[198:201], v[32:35]
	s_add_u32 m0, s45, 0x6000
	s_add_u32 s38, s36, s18
	s_addc_u32 s39, s37, s19
	global_load_lds_dwordx4 v178, s[38:39]
	v_mfma_f32_16x16x32_bf16 v[28:31], v[162:165], v[202:205], v[28:31]
	v_mfma_f32_16x16x32_bf16 v[24:27], v[162:165], v[206:209], v[24:27]
	s_add_u32 m0, s45, 0x8000
	s_add_u32 s38, s36, s22
	s_addc_u32 s39, s37, s23
	global_load_lds_dwordx4 v179, s[38:39]
	v_mfma_f32_16x16x32_bf16 v[20:23], v[166:169], v[194:197], v[20:23]
	v_mfma_f32_16x16x32_bf16 v[16:19], v[166:169], v[198:201], v[16:19]
	s_add_u32 m0, s45, 0xa000
	s_add_u32 s38, s36, s24
	s_addc_u32 s39, s37, s25
	global_load_lds_dwordx4 v179, s[38:39]
	v_mfma_f32_16x16x32_bf16 v[12:15], v[166:169], v[202:205], v[12:15]
	v_mfma_f32_16x16x32_bf16 v[8:11], v[166:169], v[206:209], v[8:11]
	s_add_u32 m0, s45, 0xc000
	s_add_u32 s38, s36, s26
	s_addc_u32 s39, s37, s27
	global_load_lds_dwordx4 v179, s[38:39]
	v_mfma_f32_16x16x32_bf16 v[4:7], v[170:173], v[194:197], v[4:7]
	v_mfma_f32_16x16x32_bf16 v[0:3], v[170:173], v[198:201], v[0:3]
	s_add_u32 m0, s45, 0xe000
	s_add_u32 s38, s36, s28
	s_addc_u32 s39, s37, s29
	global_load_lds_dwordx4 v179, s[38:39]
	v_mfma_f32_16x16x32_bf16 v[40:43], v[170:173], v[202:205], v[40:43]
	v_mfma_f32_16x16x32_bf16 v[36:39], v[170:173], v[206:209], v[36:39]
	ds_read_b128 v[158:161], v212 offset:8192
	ds_read_b128 v[162:165], v212 offset:10240
	ds_read_b128 v[166:169], v212 offset:12288
	ds_read_b128 v[170:173], v212 offset:14336
	s_waitcnt lgkmcnt(4)
	v_mfma_f32_16x16x32_bf16 v[124:127], v[142:145], v[174:177], v[124:127]
	v_mfma_f32_16x16x32_bf16 v[120:123], v[142:145], v[182:185], v[120:123]
	v_mfma_f32_16x16x32_bf16 v[116:119], v[142:145], v[186:189], v[116:119]
	v_mfma_f32_16x16x32_bf16 v[112:115], v[142:145], v[190:193], v[112:115]
	v_mfma_f32_16x16x32_bf16 v[108:111], v[146:149], v[174:177], v[108:111]
	v_mfma_f32_16x16x32_bf16 v[104:107], v[146:149], v[182:185], v[104:107]
	v_mfma_f32_16x16x32_bf16 v[100:103], v[146:149], v[186:189], v[100:103]
	v_mfma_f32_16x16x32_bf16 v[96:99], v[146:149], v[190:193], v[96:99]
	v_mfma_f32_16x16x32_bf16 v[92:95], v[150:153], v[174:177], v[92:95]
	v_mfma_f32_16x16x32_bf16 v[88:91], v[150:153], v[182:185], v[88:91]
	v_mfma_f32_16x16x32_bf16 v[84:87], v[150:153], v[186:189], v[84:87]
	v_mfma_f32_16x16x32_bf16 v[80:83], v[150:153], v[190:193], v[80:83]
	v_mfma_f32_16x16x32_bf16 v[76:79], v[154:157], v[174:177], v[76:79]
	v_mfma_f32_16x16x32_bf16 v[72:75], v[154:157], v[182:185], v[72:75]
	v_mfma_f32_16x16x32_bf16 v[68:71], v[154:157], v[186:189], v[68:71]
	v_mfma_f32_16x16x32_bf16 v[64:67], v[154:157], v[190:193], v[64:67]
	ds_read_b128 v[142:145], v213
	ds_read_b128 v[146:149], v213 offset:2048
	ds_read_b128 v[150:153], v213 offset:4096
	ds_read_b128 v[154:157], v213 offset:6144
	ds_read_b128 v[194:197], v215 offset:32768
	ds_read_b128 v[198:201], v215 offset:34816
	ds_read_b128 v[202:205], v215 offset:36864
	ds_read_b128 v[206:209], v215 offset:38912
	s_waitcnt lgkmcnt(8)
	v_mfma_f32_16x16x32_bf16 v[60:63], v[158:161], v[174:177], v[60:63]
	v_mfma_f32_16x16x32_bf16 v[56:59], v[158:161], v[182:185], v[56:59]
	v_mfma_f32_16x16x32_bf16 v[52:55], v[158:161], v[186:189], v[52:55]
	v_mfma_f32_16x16x32_bf16 v[48:51], v[158:161], v[190:193], v[48:51]
	v_mfma_f32_16x16x32_bf16 v[44:47], v[162:165], v[174:177], v[44:47]
	v_mfma_f32_16x16x32_bf16 v[32:35], v[162:165], v[182:185], v[32:35]
	v_mfma_f32_16x16x32_bf16 v[28:31], v[162:165], v[186:189], v[28:31]
	v_mfma_f32_16x16x32_bf16 v[24:27], v[162:165], v[190:193], v[24:27]
	v_mfma_f32_16x16x32_bf16 v[20:23], v[166:169], v[174:177], v[20:23]
	v_mfma_f32_16x16x32_bf16 v[16:19], v[166:169], v[182:185], v[16:19]
	v_mfma_f32_16x16x32_bf16 v[12:15], v[166:169], v[186:189], v[12:15]
	v_mfma_f32_16x16x32_bf16 v[8:11], v[166:169], v[190:193], v[8:11]
	v_mfma_f32_16x16x32_bf16 v[4:7], v[170:173], v[174:177], v[4:7]
	v_mfma_f32_16x16x32_bf16 v[0:3], v[170:173], v[182:185], v[0:3]
	v_mfma_f32_16x16x32_bf16 v[40:43], v[170:173], v[186:189], v[40:43]
	v_mfma_f32_16x16x32_bf16 v[36:39], v[170:173], v[190:193], v[36:39]
	ds_read_b128 v[158:161], v213 offset:8192
	ds_read_b128 v[162:165], v213 offset:10240
	ds_read_b128 v[166:169], v213 offset:12288
	ds_read_b128 v[170:173], v213 offset:14336
	s_waitcnt lgkmcnt(4)
	v_mfma_f32_16x16x32_bf16 v[124:127], v[142:145], v[194:197], v[124:127]
	v_mfma_f32_16x16x32_bf16 v[120:123], v[142:145], v[198:201], v[120:123]
	v_mfma_f32_16x16x32_bf16 v[116:119], v[142:145], v[202:205], v[116:119]
	v_mfma_f32_16x16x32_bf16 v[112:115], v[142:145], v[206:209], v[112:115]
	v_mfma_f32_16x16x32_bf16 v[108:111], v[146:149], v[194:197], v[108:111]
	v_mfma_f32_16x16x32_bf16 v[104:107], v[146:149], v[198:201], v[104:107]
	v_mfma_f32_16x16x32_bf16 v[100:103], v[146:149], v[202:205], v[100:103]
	v_mfma_f32_16x16x32_bf16 v[96:99], v[146:149], v[206:209], v[96:99]
	v_mfma_f32_16x16x32_bf16 v[92:95], v[150:153], v[194:197], v[92:95]
	v_mfma_f32_16x16x32_bf16 v[88:91], v[150:153], v[198:201], v[88:91]
	v_mfma_f32_16x16x32_bf16 v[84:87], v[150:153], v[202:205], v[84:87]
	v_mfma_f32_16x16x32_bf16 v[80:83], v[150:153], v[206:209], v[80:83]
	v_mfma_f32_16x16x32_bf16 v[76:79], v[154:157], v[194:197], v[76:79]
	v_mfma_f32_16x16x32_bf16 v[72:75], v[154:157], v[198:201], v[72:75]
	v_mfma_f32_16x16x32_bf16 v[68:71], v[154:157], v[202:205], v[68:71]
	v_mfma_f32_16x16x32_bf16 v[64:67], v[154:157], v[206:209], v[64:67]
	s_add_u32 s36, s36, 0x80
	s_addc_u32 s37, s37, 0
	s_add_i32 s31, s31, 1
	s_branch .Lg11_top
